# attention fast loops: packed v_pk_add_f32 split into scalar adds, +0 seed adds dropped (cost-weighted VALU / packed-vs-scalar lever)
# speedup vs baseline: 1.0096x; 1.0096x over previous
; template <bool FAST> __device__ __forceinline__ void finishSM(f32x16& p0, f32x16& p1, float alpha, float& l_reg, bf16x8& pa0, bf16x8& pa1, bf16x8& pa2, bf16x8& pa3) {
;     if (FAST) SBAR();
; #pragma unroll
;     for (int r = 0; r < 16; ++r) p1[r] = __builtin_amdgcn_exp2f(p1[r]);
;     float ps = 0;
;     if (FAST) { float s0 = 0.f, s1 = 0.f, s2 = 0.f, s3 = 0.f;
; #pragma unroll
;         for (int r = 0; r < 16; r += 4) { s0 += p0[r] + p1[r]; s1 += p0[r + 1] + p1[r + 1]; s2 += p0[r + 2] + p1[r + 2]; s3 += p0[r + 3] + p1[r + 3]; }
;         ps = (s0 + s1) + (s2 + s3); }
;     else {
; #pragma unroll
;     for (int r = 0; r < 16; ++r) ps += p0[r];
; #pragma unroll
;     for (int r = 0; r < 16; ++r) ps += p1[r];
;     }
;     if (FAST) { SBAR(); l_reg += ps; }
;     else { auto rr = __builtin_amdgcn_permlane32_swap(__float_as_uint(ps), __float_as_uint(ps), false, false);
;            ps = __uint_as_float(rr[0]) + __uint_as_float(rr[1]); l_reg = l_reg * alpha + ps; }
;     ...
;     PK4(p0, 0, pa0); PK4(p0, 8, pa1); PK4(p1, 0, pa2); PK4(p1, 8, pa3);
;     ...
; }
; template <int DQK, int NREG> __device__ __forceinline__ void qkt_mix(f32x16& p0, f32x16& p1, const char* Ks, const bf16x8* qr, const char* qs, int r32, int hi) {
;     p0 = f32x16{}; p1 = f32x16{};
; #pragma unroll
;     for (int d0 = 0; d0 < DQK / 16; ++d0) { const int cb = (d0 * 16 + hi * 8) * 2, ci = 0;
;         const bf16x8 b0 = *reinterpret_cast<const bf16x8*>(Ks + kswz<DQK>(r32, cb) + ci);
;         const bf16x8 b1 = *reinterpret_cast<const bf16x8*>(Ks + kswz<DQK>(r32, cb) + ci + 32 * (DQK * 2));
;         bf16x8 q; if (d0 < NREG) q = qr[d0]; else q = *reinterpret_cast<const bf16x8*>(qs + (d0 - NREG) * 1024);
;         p0 = __builtin_amdgcn_mfma_f32_32x32x16_bf16(b0, q, p0, 0, 0, 0);
;         p1 = __builtin_amdgcn_mfma_f32_32x32x16_bf16(b1, q, p1, 0, 0, 0); }
; }
; template <int DQK> __device__ __forceinline__ void qkt_ld(f32x16& p0, f32x16& p1, const char* Ks, const bf16_t* qw, int r32, int hi) {
;     p0 = f32x16{}; p1 = f32x16{};
; #pragma unroll
;     for (int d0 = 0; d0 < DQK / 16; ++d0) { const int cb = (d0 * 16 + hi * 8) * 2, ci = 0;
;         const bf16x8 q = *(const bf16x8*)(qw + d0 * 16);
;         const bf16x8 b0 = *reinterpret_cast<const bf16x8*>(Ks + kswz<DQK>(r32, cb) + ci);
;         const bf16x8 b1 = *reinterpret_cast<const bf16x8*>(Ks + kswz<DQK>(r32, cb) + ci + 32 * (DQK * 2));
.LBB0_529:
	s_add_u32 s76, s44, 0xfffa0000
	s_addc_u32 s77, s45, -1
	v_lshl_add_u64 v[80:81], s[76:77], 0, v[160:161]
	s_mov_b32 s1, m0
	s_mov_b32 m0, s53
	s_nop 0
	global_load_lds_dwordx4 v[80:81], off
	s_mov_b32 m0, s1
	v_lshl_add_u64 v[80:81], s[76:77], 0, v[162:163]
	s_mov_b32 s1, m0
	s_mov_b32 m0, s54
	s_nop 0
	global_load_lds_dwordx4 v[80:81], off
	s_mov_b32 m0, s1
	s_cmp_lg_u32 0, -1
	s_cselect_b32 s1, 0, 0
	v_lshl_add_u64 v[200:201], s[44:45], 0, v[164:165]
	s_add_i32 s1, s1, s52
	v_lshl_add_u64 v[80:81], v[200:201], 0, s[20:21]
	s_add_i32 s75, s1, 0x4000
	s_mov_b32 s76, m0
	s_mov_b32 m0, s75
	s_nop 0
	global_load_lds_dwordx4 v[80:81], off
	s_mov_b32 m0, s76
	v_lshl_add_u64 v[80:81], v[200:201], 0, s[22:23]
	s_addk_i32 s1, 0x4400
	s_mov_b32 s75, m0
	s_mov_b32 m0, s1
	s_nop 0
	global_load_lds_dwordx4 v[80:81], off
	s_mov_b32 m0, s75
	ds_read_b128 v[80:83], v231 offset:49152
	ds_read_b128 v[156:159], v231 offset:57344
	ds_read_b128 v[240:243], v232 offset:49152
	ds_read_b128 v[152:155], v232 offset:57344
	ds_read_b128 v[244:247], v233 offset:49152
	ds_read_b128 v[148:151], v233 offset:57344
	ds_read_b128 v[248:251], v234 offset:49152
	ds_read_b128 v[144:147], v234 offset:57344
	s_waitcnt lgkmcnt(7)
	v_mfma_f32_32x32x16_bf16 v[80:95], v[80:83], v[116:119], 0
	s_waitcnt lgkmcnt(5)
	v_mfma_f32_32x32x16_bf16 v[80:95], v[240:243], v[112:115], v[80:95]
	ds_read_b128 v[240:243], v235 offset:49152
	ds_read_b128 v[140:143], v235 offset:57344
	v_exp_f32_e32 v217, v64
	v_exp_f32_e32 v215, v65
	s_waitcnt lgkmcnt(5)
	v_mfma_f32_32x32x16_bf16 v[80:95], v[244:247], v[108:111], v[80:95]
	ds_read_b128 v[244:247], v236 offset:49152
	ds_read_b128 v[136:139], v236 offset:57344
	v_exp_f32_e32 v216, v66
	v_exp_f32_e32 v214, v67
	s_waitcnt lgkmcnt(5)
	v_mfma_f32_32x32x16_bf16 v[80:95], v[248:251], v[104:107], v[80:95]
	ds_read_b128 v[248:251], v237 offset:49152
	ds_read_b128 v[124:127], v229
	ds_read_b128 v[132:135], v237 offset:57344
	v_exp_f32_e32 v213, v68
	v_exp_f32_e32 v211, v69
	s_waitcnt lgkmcnt(6)
	v_mfma_f32_32x32x16_bf16 v[80:95], v[240:243], v[100:103], v[80:95]
	ds_read_b128 v[240:243], v238 offset:49152
	ds_read_b128 v[120:123], v229 offset:1024
	ds_read_b128 v[128:131], v238 offset:57344
	v_exp_f32_e32 v212, v70
	v_exp_f32_e32 v210, v71
	s_waitcnt lgkmcnt(7)
	v_mfma_f32_32x32x16_bf16 v[80:95], v[244:247], v[96:99], v[80:95]
	v_exp_f32_e32 v209, v72
	v_exp_f32_e32 v207, v73
	v_exp_f32_e32 v208, v74
	s_waitcnt lgkmcnt(4)
	v_mfma_f32_32x32x16_bf16 v[80:95], v[248:251], v[124:127], v[80:95]
	v_exp_f32_e32 v206, v75
	v_exp_f32_e32 v205, v76
	v_exp_f32_e32 v203, v77
	s_waitcnt lgkmcnt(1)
	v_mfma_f32_32x32x16_bf16 v[80:95], v[240:243], v[120:123], v[80:95]
	v_exp_f32_e32 v204, v78
	v_exp_f32_e32 v202, v79
	ds_read_b64_tr_b16 v[184:185], v228 offset:0
	ds_read_b64_tr_b16 v[186:187], v228 offset:0x800
	ds_read_b64_tr_b16 v[188:189], v228 offset:0x1000
	ds_read_b64_tr_b16 v[190:191], v228 offset:0x1800
	ds_read_b64_tr_b16 v[192:193], v228 offset:0x2000
	ds_read_b64_tr_b16 v[194:195], v228 offset:0x2800
	ds_read_b64_tr_b16 v[196:197], v228 offset:0x3000
	ds_read_b64_tr_b16 v[198:199], v228 offset:0x3800
	v_cvt_pk_bf16_f32 v64, v183, v181
	v_cvt_pk_bf16_f32 v65, v182, v180
	v_cvt_pk_bf16_f32 v66, v179, v177
	v_cvt_pk_bf16_f32 v67, v178, v176
	v_cvt_pk_bf16_f32 v68, v175, v173
	v_cvt_pk_bf16_f32 v69, v174, v172
	v_cvt_pk_bf16_f32 v70, v171, v169
	v_cvt_pk_bf16_f32 v71, v170, v168
	v_cvt_pk_bf16_f32 v72, v217, v215
	v_cvt_pk_bf16_f32 v73, v216, v214
	v_cvt_pk_bf16_f32 v74, v213, v211
	v_cvt_pk_bf16_f32 v75, v212, v210
	v_cvt_pk_bf16_f32 v76, v209, v207
	v_cvt_pk_bf16_f32 v77, v208, v206
	v_cvt_pk_bf16_f32 v78, v205, v203
	v_cvt_pk_bf16_f32 v79, v204, v202
	s_nop 0
	v_permlane32_swap_b32_e32 v64, v66
	v_permlane32_swap_b32_e32 v65, v67
	v_permlane32_swap_b32_e32 v68, v70
	v_permlane32_swap_b32_e32 v69, v71
	v_permlane32_swap_b32_e32 v72, v74
	v_permlane32_swap_b32_e32 v73, v75
	v_permlane32_swap_b32_e32 v76, v78
	v_permlane32_swap_b32_e32 v77, v79
	s_waitcnt lgkmcnt(0)
	s_nop 0
	v_mfma_f32_32x32x16_bf16 v[0:15], v[64:67], v[184:187], v[0:15]
	ds_read_b64_tr_b16 v[184:185], v228 offset:0x200
	ds_read_b64_tr_b16 v[186:187], v228 offset:0xa00
	v_mfma_f32_32x32x16_bf16 v[0:15], v[68:71], v[188:191], v[0:15]
	ds_read_b64_tr_b16 v[188:189], v228 offset:0x1200
	ds_read_b64_tr_b16 v[190:191], v228 offset:0x1a00
	v_mfma_f32_32x32x16_bf16 v[0:15], v[72:75], v[192:195], v[0:15]
	ds_read_b64_tr_b16 v[192:193], v228 offset:0x2200
	ds_read_b64_tr_b16 v[194:195], v228 offset:0x2a00
	ds_read_b64_tr_b16 v[240:241], v228 offset:0x3200
	ds_read_b64_tr_b16 v[242:243], v228 offset:0x3a00
	s_waitcnt lgkmcnt(0)
	v_mfma_f32_32x32x16_bf16 v[0:15], v[76:79], v[196:199], v[0:15]
	v_mfma_f32_32x32x16_bf16 v[16:31], v[64:67], v[184:187], v[16:31]
	ds_read_b64_tr_b16 v[184:185], v228 offset:0x400
	ds_read_b64_tr_b16 v[186:187], v228 offset:0xc00
	v_mfma_f32_32x32x16_bf16 v[16:31], v[68:71], v[188:191], v[16:31]
	ds_read_b64_tr_b16 v[188:189], v228 offset:0x1400
	ds_read_b64_tr_b16 v[190:191], v228 offset:0x1c00
	v_mfma_f32_32x32x16_bf16 v[16:31], v[72:75], v[192:195], v[16:31]
	ds_read_b64_tr_b16 v[192:193], v228 offset:0x2400
	ds_read_b64_tr_b16 v[194:195], v228 offset:0x2c00
	ds_read_b64_tr_b16 v[196:197], v228 offset:0x3400
	ds_read_b64_tr_b16 v[198:199], v228 offset:0x3c00
	s_waitcnt lgkmcnt(0)
	v_mfma_f32_32x32x16_bf16 v[16:31], v[76:79], v[240:243], v[16:31]
	v_mfma_f32_32x32x16_bf16 v[32:47], v[64:67], v[184:187], v[32:47]
	ds_read_b64_tr_b16 v[184:185], v228 offset:0x600
	ds_read_b64_tr_b16 v[186:187], v228 offset:0xe00
	v_mfma_f32_32x32x16_bf16 v[32:47], v[68:71], v[188:191], v[32:47]
	ds_read_b64_tr_b16 v[188:189], v228 offset:0x1600
	ds_read_b64_tr_b16 v[190:191], v228 offset:0x1e00
	v_mfma_f32_32x32x16_bf16 v[32:47], v[72:75], v[192:195], v[32:47]
	ds_read_b64_tr_b16 v[192:193], v228 offset:0x2600
	ds_read_b64_tr_b16 v[194:195], v228 offset:0x2e00
	ds_read_b64_tr_b16 v[240:241], v228 offset:0x3600
	ds_read_b64_tr_b16 v[242:243], v228 offset:0x3e00
	s_waitcnt lgkmcnt(0)
	v_mfma_f32_32x32x16_bf16 v[32:47], v[76:79], v[196:199], v[32:47]
	s_cmp_ge_u32 s100, 0x100
	s_cbranch_scc1 .Latt_a_late_half
; #define SBAR() __builtin_amdgcn_sched_barrier(0)
; #define DMA_K(t, buf) do { const char* kb_ = (const char*)Kh + (size_t)(t) * TILEB; \
;         glds16(kb_ + ksrc[0], (unsigned)__builtin_amdgcn_readfirstlane(lds0 + OFF_K + (buf) * SHM_K + (DQK == 128 ? widu * 2048 : widu * 1024))); \
;         if (DQK == 128) glds16(kb_ + ksrc[1], (unsigned)__builtin_amdgcn_readfirstlane(lds0 + OFF_K + (buf) * SHM_K + widu * 2048 + 1024)); } while (0)
; #define DMA_V(t, buf) do { const char* vb_ = (const char*)Vh + (size_t)(t) * TILEB; \
;         glds16(vb_ + vsrc[0], (unsigned)__builtin_amdgcn_readfirstlane(lds0 + (buf) * SHM_V + widu * 2048)); \
;         glds16(vb_ + vsrc[1], (unsigned)__builtin_amdgcn_readfirstlane(lds0 + (buf) * SHM_V + widu * 2048 + 1024)); } while (0)
; #define WBAR0() do { asm volatile("s_waitcnt vmcnt(0)" ::: "memory"); __syncthreads(); } while (0)
; #define EXPH(P) do { _Pragma("unroll") for (int r = 0; r < 16; ++r) P[r] = __builtin_amdgcn_exp2f(P[r]); } while (0)
; template <bool FAST> __device__ __forceinline__ void finishSM(f32x16& p0, f32x16& p1, float alpha, float& l_reg, bf16x8& pa0, bf16x8& pa1, bf16x8& pa2, bf16x8& pa3) {
;     ...
;     for (int r = 0; r < 16; ++r) p1[r] = __builtin_amdgcn_exp2f(p1[r]);
;     float ps = 0;
;     if (FAST) { float s0 = 0.f, s1 = 0.f, s2 = 0.f, s3 = 0.f;
; #pragma unroll
;         for (int r = 0; r < 16; r += 4) { s0 += p0[r] + p1[r]; s1 += p0[r + 1] + p1[r + 1]; s2 += p0[r + 2] + p1[r + 2]; s3 += p0[r + 3] + p1[r + 3]; }
;         ps = (s0 + s1) + (s2 + s3); }
;     ...
;         DMA_K(k + 1, 0); DMA_V(k, 1); SBAR();
;         if (isY) { EXPH(pA0); }
;         SBAR(); qkt_mix<DQK, NREG>(pB0, pB1, K_lds + SHM_K, qr, qs, r32, hi);
;         finishSM<true>(pA0, pA1, dummy_a, l_reg, pa0, pa1, pa2, pa3); SBAR();
;         pv_d0(o, vb0, pa0, pa1, pa2, pa3);
;         if (!isY) { EXPH(pB0); }
;         WBAR0();
	v_mfma_f32_32x32x16_bf16 v[48:63], v[64:67], v[184:187], v[48:63]
	v_exp_f32_e32 v199, v80
	v_exp_f32_e32 v197, v81
	v_exp_f32_e32 v198, v82
	v_exp_f32_e32 v196, v83
	v_add_f32_e32 v80, v182, v216
	v_add_f32_e32 v81, v183, v217
	v_add_f32_e32 v82, v180, v214
	v_add_f32_e32 v83, v181, v215
	v_mfma_f32_32x32x16_bf16 v[48:63], v[68:71], v[188:191], v[48:63]
	v_exp_f32_e32 v191, v88
	v_exp_f32_e32 v189, v89
	v_exp_f32_e32 v190, v90
	v_exp_f32_e32 v188, v91
	v_add_f32_e32 v88, v174, v208
	v_add_f32_e32 v89, v175, v209
	v_add_f32_e32 v90, v172, v206
	v_add_f32_e32 v91, v173, v207
	v_mfma_f32_32x32x16_bf16 v[48:63], v[72:75], v[192:195], v[48:63]
	v_exp_f32_e32 v195, v84
	v_exp_f32_e32 v193, v85
	v_exp_f32_e32 v194, v86
	v_exp_f32_e32 v192, v87
	v_add_f32_e32 v84, v178, v212
	v_add_f32_e32 v85, v179, v213
	v_add_f32_e32 v86, v176, v210
	v_add_f32_e32 v87, v177, v211
	v_add_f32_e32 v80, v84, v80
	v_add_f32_e32 v81, v85, v81
	v_mfma_f32_32x32x16_bf16 v[48:63], v[76:79], v[240:243], v[48:63]
	v_add_f32_e64 v82, v86, v82
	v_add_f32_e64 v83, v87, v83
	v_exp_f32_e32 v187, v92
	v_exp_f32_e32 v185, v93
	v_exp_f32_e32 v186, v94
	v_exp_f32_e32 v184, v95
	v_add_f32_e32 v92, v170, v204
	v_add_f32_e32 v93, v171, v205
	v_add_f32_e32 v94, v168, v202
	v_add_f32_e32 v95, v169, v203
	v_mfma_f32_32x32x16_bf16 v[64:79], v[156:159], v[116:119], 0
	v_add_f32_e64 v80, v88, v80
	v_add_f32_e64 v81, v89, v81
	v_add_f32_e64 v82, v90, v82
	v_add_f32_e64 v83, v91, v83
	v_add_f32_e64 v80, v92, v80
	v_add_f32_e64 v81, v93, v81
	v_add_f32_e32 v82, v94, v82
	v_add_f32_e32 v83, v95, v83
	s_waitcnt vmcnt(0)
	s_waitcnt lgkmcnt(0)
	v_add_f32_e32 v80, v82, v80
	v_add_f32_e32 v81, v83, v81
	v_mfma_f32_32x32x16_bf16 v[64:79], v[152:155], v[112:115], v[64:79]
	v_add_f32_e32 v216, v80, v81
	s_barrier
	v_lshl_add_u64 v[80:81], s[44:45], 0, v[160:161]
	s_mov_b32 s1, m0
	s_mov_b32 m0, s73
	s_nop 0
	global_load_lds_dwordx4 v[80:81], off
	s_mov_b32 m0, s1
	v_lshl_add_u64 v[80:81], s[44:45], 0, v[162:163]
	s_mov_b32 s1, m0
	s_mov_b32 m0, s74
	s_nop 0
	global_load_lds_dwordx4 v[80:81], off
	s_mov_b32 m0, s1
	v_mfma_f32_32x32x16_bf16 v[64:79], v[148:151], v[108:111], v[64:79]
	v_lshl_add_u64 v[80:81], v[200:201], 0, s[26:27]
	s_mov_b32 s1, m0
	s_mov_b32 m0, s72
	s_nop 0
	global_load_lds_dwordx4 v[80:81], off
	s_mov_b32 m0, s1
	v_lshl_add_u64 v[80:81], v[200:201], 0, s[28:29]
	s_mov_b32 s1, m0
	s_mov_b32 m0, s0
	s_nop 0
	global_load_lds_dwordx4 v[80:81], off
	s_mov_b32 m0, s1
	v_mfma_f32_32x32x16_bf16 v[64:79], v[144:147], v[104:107], v[64:79]
	v_mfma_f32_32x32x16_bf16 v[64:79], v[140:143], v[100:103], v[64:79]
	v_mfma_f32_32x32x16_bf16 v[64:79], v[136:139], v[96:99], v[64:79]
	v_mfma_f32_32x32x16_bf16 v[64:79], v[132:135], v[124:127], v[64:79]
	v_mfma_f32_32x32x16_bf16 v[64:79], v[128:131], v[120:123], v[64:79]
	s_branch .Latt_a_join_half
.Latt_a_late_half:
	v_mfma_f32_32x32x16_bf16 v[48:63], v[64:67], v[184:187], v[48:63]
	v_mfma_f32_32x32x16_bf16 v[48:63], v[68:71], v[188:191], v[48:63]
	v_mfma_f32_32x32x16_bf16 v[48:63], v[72:75], v[192:195], v[48:63]
	v_mfma_f32_32x32x16_bf16 v[48:63], v[76:79], v[240:243], v[48:63]
	v_mfma_f32_32x32x16_bf16 v[64:79], v[156:159], v[116:119], 0
	s_waitcnt vmcnt(0)
	s_waitcnt lgkmcnt(0)
	v_mfma_f32_32x32x16_bf16 v[64:79], v[152:155], v[112:115], v[64:79]
	s_barrier
	v_lshl_add_u64 v[240:241], s[44:45], 0, v[160:161]
	s_mov_b32 s1, m0
	s_mov_b32 m0, s73
	s_nop 0
	global_load_lds_dwordx4 v[240:241], off
	s_mov_b32 m0, s1
	v_lshl_add_u64 v[240:241], s[44:45], 0, v[162:163]
	s_mov_b32 s1, m0
	s_mov_b32 m0, s74
	s_nop 0
	global_load_lds_dwordx4 v[240:241], off
	s_mov_b32 m0, s1
	v_mfma_f32_32x32x16_bf16 v[64:79], v[148:151], v[108:111], v[64:79]
	v_exp_f32_e32 v199, v80
	v_exp_f32_e32 v197, v81
	v_exp_f32_e32 v198, v82
	v_exp_f32_e32 v196, v83
	v_add_f32_e32 v80, v182, v216
	v_add_f32_e32 v81, v183, v217
	v_add_f32_e32 v82, v180, v214
	v_add_f32_e32 v83, v181, v215
	v_lshl_add_u64 v[240:241], v[200:201], 0, s[26:27]
	s_mov_b32 s1, m0
	s_mov_b32 m0, s72
	s_nop 0
	global_load_lds_dwordx4 v[240:241], off
	s_mov_b32 m0, s1
	v_lshl_add_u64 v[240:241], v[200:201], 0, s[28:29]
	s_mov_b32 s1, m0
	s_mov_b32 m0, s0
	s_nop 0
	global_load_lds_dwordx4 v[240:241], off
	s_mov_b32 m0, s1
	v_mfma_f32_32x32x16_bf16 v[64:79], v[144:147], v[104:107], v[64:79]
	v_exp_f32_e32 v191, v88
	v_exp_f32_e32 v189, v89
	v_exp_f32_e32 v190, v90
	v_exp_f32_e32 v188, v91
	v_add_f32_e32 v88, v174, v208
	v_add_f32_e32 v89, v175, v209
	v_add_f32_e32 v90, v172, v206
	v_add_f32_e32 v91, v173, v207
	v_exp_f32_e32 v195, v84
	v_exp_f32_e32 v193, v85
	v_mfma_f32_32x32x16_bf16 v[64:79], v[140:143], v[100:103], v[64:79]
	v_exp_f32_e32 v194, v86
	v_exp_f32_e32 v192, v87
	v_add_f32_e32 v84, v178, v212
	v_add_f32_e32 v85, v179, v213
	v_add_f32_e32 v86, v176, v210
	v_add_f32_e32 v87, v177, v211
	v_add_f32_e32 v80, v84, v80
	v_add_f32_e32 v81, v85, v81
	v_add_f32_e64 v82, v86, v82
	v_add_f32_e64 v83, v87, v83
	v_exp_f32_e32 v187, v92
	v_mfma_f32_32x32x16_bf16 v[64:79], v[136:139], v[96:99], v[64:79]
	v_exp_f32_e32 v185, v93
	v_exp_f32_e32 v186, v94
	v_exp_f32_e32 v184, v95
	v_add_f32_e32 v92, v170, v204
	v_add_f32_e32 v93, v171, v205
	v_add_f32_e32 v94, v168, v202
	v_add_f32_e32 v95, v169, v203
	v_add_f32_e64 v80, v88, v80
	v_add_f32_e64 v81, v89, v81
	v_add_f32_e64 v82, v90, v82
	v_mfma_f32_32x32x16_bf16 v[64:79], v[132:135], v[124:127], v[64:79]
	v_add_f32_e64 v83, v91, v83
	v_add_f32_e64 v80, v92, v80
	v_add_f32_e64 v81, v93, v81
	v_add_f32_e32 v82, v94, v82
	v_add_f32_e32 v83, v95, v83
	s_nop 0
	v_add_f32_e32 v80, v82, v80
	v_add_f32_e32 v81, v83, v81
	s_nop 0
	v_add_f32_e32 v216, v80, v81
	v_mfma_f32_32x32x16_bf16 v[64:79], v[128:131], v[120:123], v[64:79]
	s_branch .Latt_a_join_half
; #define SBAR() __builtin_amdgcn_sched_barrier(0)
; #define DMA_K(t, buf) do { const char* kb_ = (const char*)Kh + (size_t)(t) * TILEB; \
;         glds16(kb_ + ksrc[0], (unsigned)__builtin_amdgcn_readfirstlane(lds0 + OFF_K + (buf) * SHM_K + (DQK == 128 ? widu * 2048 : widu * 1024))); \
;         if (DQK == 128) glds16(kb_ + ksrc[1], (unsigned)__builtin_amdgcn_readfirstlane(lds0 + OFF_K + (buf) * SHM_K + widu * 2048 + 1024)); } while (0)
; #define DMA_V(t, buf) do { const char* vb_ = (const char*)Vh + (size_t)(t) * TILEB; \
;         glds16(vb_ + vsrc[0], (unsigned)__builtin_amdgcn_readfirstlane(lds0 + (buf) * SHM_V + widu * 2048)); \
;         glds16(vb_ + vsrc[1], (unsigned)__builtin_amdgcn_readfirstlane(lds0 + (buf) * SHM_V + widu * 2048 + 1024)); } while (0)
; #define EXPH(P) do { _Pragma("unroll") for (int r = 0; r < 16; ++r) P[r] = __builtin_amdgcn_exp2f(P[r]); } while (0)
; template <bool FAST> __device__ __forceinline__ void finishSM(f32x16& p0, f32x16& p1, float alpha, float& l_reg, bf16x8& pa0, bf16x8& pa1, bf16x8& pa2, bf16x8& pa3) {
;     if (FAST) SBAR();
; #pragma unroll
;     for (int r = 0; r < 16; ++r) p1[r] = __builtin_amdgcn_exp2f(p1[r]);
;     float ps = 0;
;     if (FAST) { float s0 = 0.f, s1 = 0.f, s2 = 0.f, s3 = 0.f;
; #pragma unroll
;         for (int r = 0; r < 16; r += 4) { s0 += p0[r] + p1[r]; s1 += p0[r + 1] + p1[r + 1]; s2 += p0[r + 2] + p1[r + 2]; s3 += p0[r + 3] + p1[r + 3]; }
;         ps = (s0 + s1) + (s2 + s3); }
;     else {
; #pragma unroll
;     for (int r = 0; r < 16; ++r) ps += p0[r];
; #pragma unroll
;     for (int r = 0; r < 16; ++r) ps += p1[r];
;     }
;     if (FAST) { SBAR(); l_reg += ps; }
;     else { auto rr = __builtin_amdgcn_permlane32_swap(__float_as_uint(ps), __float_as_uint(ps), false, false);
;            ps = __uint_as_float(rr[0]) + __uint_as_float(rr[1]); l_reg = l_reg * alpha + ps; }
;     ...
;     PK4(p0, 0, pa0); PK4(p0, 8, pa1); PK4(p1, 0, pa2); PK4(p1, 8, pa3);
;     ...
; }
;     ...
;         DMA_K(k + 2, 1); DMA_V(k + 1, 0); SBAR();
;         if (isY) { EXPH(pB0); }
;         SBAR(); qkt_mix<DQK, NREG>(pA0, pA1, K_lds, qr, qs, r32, hi);
;         finishSM<true>(pB0, pB1, dummy_a, l_reg, pa0, pa1, pa2, pa3); SBAR();
;         pv_d0(o, vb0 + SHM_V, pa0, pa1, pa2, pa3);
;         if (!isY) { EXPH(pA0); }
.Latt_a_join_half:
	ds_read_b128 v[80:83], v231 offset:32768
	ds_read_b128 v[148:151], v231 offset:40960
	ds_read_b128 v[240:243], v232 offset:32768
	ds_read_b128 v[152:155], v232 offset:40960
	ds_read_b128 v[244:247], v233 offset:32768
	ds_read_b128 v[156:159], v233 offset:40960
	ds_read_b128 v[248:251], v234 offset:32768
	ds_read_b128 v[144:147], v234 offset:40960
	s_waitcnt lgkmcnt(7)
	v_mfma_f32_32x32x16_bf16 v[80:95], v[80:83], v[116:119], 0
	s_waitcnt lgkmcnt(5)
	v_mfma_f32_32x32x16_bf16 v[80:95], v[240:243], v[112:115], v[80:95]
	ds_read_b128 v[240:243], v235 offset:32768
	ds_read_b128 v[140:143], v235 offset:40960
	s_waitcnt lgkmcnt(5)
	v_mfma_f32_32x32x16_bf16 v[80:95], v[244:247], v[108:111], v[80:95]
	ds_read_b128 v[244:247], v236 offset:32768
	ds_read_b128 v[136:139], v236 offset:40960
	v_exp_f32_e32 v215, v64
	v_exp_f32_e32 v213, v65
	s_waitcnt lgkmcnt(5)
	v_mfma_f32_32x32x16_bf16 v[80:95], v[248:251], v[104:107], v[80:95]
	ds_read_b128 v[248:251], v237 offset:32768
	ds_read_b128 v[124:127], v229
	ds_read_b128 v[128:131], v237 offset:40960
	v_exp_f32_e32 v214, v66
	v_exp_f32_e32 v212, v67
	s_waitcnt lgkmcnt(6)
	v_mfma_f32_32x32x16_bf16 v[80:95], v[240:243], v[100:103], v[80:95]
	ds_read_b128 v[240:243], v238 offset:32768
	ds_read_b128 v[120:123], v229 offset:1024
	ds_read_b128 v[132:135], v238 offset:40960
	v_exp_f32_e32 v211, v68
	v_exp_f32_e32 v209, v69
	v_exp_f32_e32 v210, v70
	s_waitcnt lgkmcnt(7)
	v_mfma_f32_32x32x16_bf16 v[80:95], v[244:247], v[96:99], v[80:95]
	v_exp_f32_e32 v208, v71
	v_exp_f32_e32 v207, v72
	v_exp_f32_e32 v205, v73
	s_waitcnt lgkmcnt(4)
	v_mfma_f32_32x32x16_bf16 v[80:95], v[248:251], v[124:127], v[80:95]
	v_exp_f32_e32 v206, v74
	v_exp_f32_e32 v204, v75
	v_exp_f32_e32 v203, v76
	s_waitcnt lgkmcnt(1)
	v_mfma_f32_32x32x16_bf16 v[80:95], v[240:243], v[120:123], v[80:95]
	v_exp_f32_e32 v201, v77
	v_exp_f32_e32 v202, v78
	v_exp_f32_e32 v200, v79
	ds_read_b64_tr_b16 v[68:69], v227 offset:0
	ds_read_b64_tr_b16 v[70:71], v227 offset:0x800
	ds_read_b64_tr_b16 v[72:73], v227 offset:0x1000
	ds_read_b64_tr_b16 v[74:75], v227 offset:0x1800
	ds_read_b64_tr_b16 v[76:77], v227 offset:0x2000
	ds_read_b64_tr_b16 v[78:79], v227 offset:0x2800
	ds_read_b64_tr_b16 v[180:181], v227 offset:0x3000
	ds_read_b64_tr_b16 v[182:183], v227 offset:0x3800
	v_cvt_pk_bf16_f32 v64, v199, v197
	v_cvt_pk_bf16_f32 v65, v198, v196
	v_cvt_pk_bf16_f32 v66, v195, v193
	v_cvt_pk_bf16_f32 v67, v194, v192
	v_cvt_pk_bf16_f32 v168, v191, v189
	v_cvt_pk_bf16_f32 v169, v190, v188
	v_cvt_pk_bf16_f32 v170, v187, v185
	v_cvt_pk_bf16_f32 v171, v186, v184
	v_cvt_pk_bf16_f32 v172, v215, v213
	v_cvt_pk_bf16_f32 v173, v214, v212
	v_cvt_pk_bf16_f32 v174, v211, v209
	v_cvt_pk_bf16_f32 v175, v210, v208
	v_cvt_pk_bf16_f32 v176, v207, v205
	v_cvt_pk_bf16_f32 v177, v206, v204
	v_cvt_pk_bf16_f32 v178, v203, v201
	v_cvt_pk_bf16_f32 v179, v202, v200
	s_nop 0
	v_permlane32_swap_b32_e32 v64, v66
	v_permlane32_swap_b32_e32 v65, v67
	v_permlane32_swap_b32_e32 v168, v170
	v_permlane32_swap_b32_e32 v169, v171
	v_permlane32_swap_b32_e32 v172, v174
	v_permlane32_swap_b32_e32 v173, v175
	v_permlane32_swap_b32_e32 v176, v178
	v_permlane32_swap_b32_e32 v177, v179
	s_waitcnt lgkmcnt(0)
	s_nop 0
	v_mfma_f32_32x32x16_bf16 v[0:15], v[64:67], v[68:71], v[0:15]
	ds_read_b64_tr_b16 v[68:69], v227 offset:0x200
	ds_read_b64_tr_b16 v[70:71], v227 offset:0xa00
	v_mfma_f32_32x32x16_bf16 v[0:15], v[168:171], v[72:75], v[0:15]
	ds_read_b64_tr_b16 v[72:73], v227 offset:0x1200
	ds_read_b64_tr_b16 v[74:75], v227 offset:0x1a00
	v_mfma_f32_32x32x16_bf16 v[0:15], v[172:175], v[76:79], v[0:15]
	ds_read_b64_tr_b16 v[76:77], v227 offset:0x2200
	ds_read_b64_tr_b16 v[78:79], v227 offset:0x2a00
	ds_read_b64_tr_b16 v[240:241], v227 offset:0x3200
	ds_read_b64_tr_b16 v[242:243], v227 offset:0x3a00
	s_waitcnt lgkmcnt(0)
	v_mfma_f32_32x32x16_bf16 v[0:15], v[176:179], v[180:183], v[0:15]
	v_mfma_f32_32x32x16_bf16 v[16:31], v[64:67], v[68:71], v[16:31]
	ds_read_b64_tr_b16 v[68:69], v227 offset:0x400
	ds_read_b64_tr_b16 v[70:71], v227 offset:0xc00
	v_mfma_f32_32x32x16_bf16 v[16:31], v[168:171], v[72:75], v[16:31]
	ds_read_b64_tr_b16 v[72:73], v227 offset:0x1400
	ds_read_b64_tr_b16 v[74:75], v227 offset:0x1c00
	v_mfma_f32_32x32x16_bf16 v[16:31], v[172:175], v[76:79], v[16:31]
	ds_read_b64_tr_b16 v[76:77], v227 offset:0x2400
	ds_read_b64_tr_b16 v[78:79], v227 offset:0x2c00
	ds_read_b64_tr_b16 v[180:181], v227 offset:0x3400
	ds_read_b64_tr_b16 v[182:183], v227 offset:0x3c00
	s_waitcnt lgkmcnt(0)
	v_mfma_f32_32x32x16_bf16 v[16:31], v[176:179], v[240:243], v[16:31]
	v_mfma_f32_32x32x16_bf16 v[32:47], v[64:67], v[68:71], v[32:47]
	ds_read_b64_tr_b16 v[68:69], v227 offset:0x600
	ds_read_b64_tr_b16 v[70:71], v227 offset:0xe00
	ds_read_b64_tr_b16 v[240:241], v227 offset:0x1600
	ds_read_b64_tr_b16 v[242:243], v227 offset:0x1e00
	ds_read_b64_tr_b16 v[244:245], v227 offset:0x2600
	ds_read_b64_tr_b16 v[246:247], v227 offset:0x2e00
	ds_read_b64_tr_b16 v[248:249], v227 offset:0x3600
	v_mfma_f32_32x32x16_bf16 v[32:47], v[168:171], v[72:75], v[32:47]
	ds_read_b64_tr_b16 v[250:251], v227 offset:0x3e00
	s_waitcnt lgkmcnt(0)
	v_mfma_f32_32x32x16_bf16 v[32:47], v[172:175], v[76:79], v[32:47]
	v_mfma_f32_32x32x16_bf16 v[32:47], v[176:179], v[180:183], v[32:47]
	v_mfma_f32_32x32x16_bf16 v[48:63], v[64:67], v[68:71], v[48:63]
	v_exp_f32_e32 v183, v80
	v_exp_f32_e32 v181, v81
	v_exp_f32_e32 v182, v82
	v_exp_f32_e32 v180, v83
	v_add_f32_e32 v80, v198, v214
	v_add_f32_e32 v81, v199, v215
	v_add_f32_e32 v82, v196, v212
	v_add_f32_e32 v83, v197, v213
	v_mfma_f32_32x32x16_bf16 v[64:79], v[148:151], v[116:119], 0
	s_add_i32 s55, s55, 2
	s_waitcnt vmcnt(0)
	s_add_u32 s44, s44, 0xc0000
	s_addc_u32 s45, s45, 0
	s_cmp_gt_u32 s55, 64
	s_waitcnt lgkmcnt(0)
	v_mfma_f32_32x32x16_bf16 v[64:79], v[152:155], v[112:115], v[64:79]
	s_barrier
; #define SBAR() __builtin_amdgcn_sched_barrier(0)
; #define DMA_V(t, buf) do { const char* vb_ = (const char*)Vh + (size_t)(t) * TILEB; \
;         glds16(vb_ + vsrc[0], (unsigned)__builtin_amdgcn_readfirstlane(lds0 + (buf) * SHM_V + widu * 2048)); \
;         glds16(vb_ + vsrc[1], (unsigned)__builtin_amdgcn_readfirstlane(lds0 + (buf) * SHM_V + widu * 2048 + 1024)); } while (0)
; #define WBAR0() do { asm volatile("s_waitcnt vmcnt(0)" ::: "memory"); __syncthreads(); } while (0)
; #define EXPH(P) do { _Pragma("unroll") for (int r = 0; r < 16; ++r) P[r] = __builtin_amdgcn_exp2f(P[r]); } while (0)
;     ...
;         if (!isY) { EXPH(pA0); }
;         WBAR0();
;     }
;     DMA_V(NT - 1, 1); SBAR();
;     if (isY) { EXPH(pA0); }
;     SBAR(); qkt_mix<DQK, NREG>(pB0, pB1, K_lds + SHM_K, qr, qs, r32, hi);
;     finishSM<true>(pA0, pA1, dummy_a, l_reg, pa0, pa1, pa2, pa3); SBAR();
;     pv_d0(o, vb0, pa0, pa1, pa2, pa3);
	v_mfma_f32_32x32x16_bf16 v[64:79], v[156:159], v[108:111], v[64:79]
	v_mfma_f32_32x32x16_bf16 v[64:79], v[144:147], v[104:107], v[64:79]
	v_mfma_f32_32x32x16_bf16 v[64:79], v[140:143], v[100:103], v[64:79]
	v_add_f32_e32 v140, v230, v216
	v_mfma_f32_32x32x16_bf16 v[48:63], v[168:171], v[240:243], v[48:63]
	v_exp_f32_e32 v171, v92
	v_exp_f32_e32 v169, v93
	v_exp_f32_e32 v170, v94
	v_exp_f32_e32 v168, v95
	v_add_f32_e32 v92, v186, v202
	v_add_f32_e32 v93, v187, v203
	v_add_f32_e32 v94, v184, v200
	v_add_f32_e32 v95, v185, v201
	v_mfma_f32_32x32x16_bf16 v[64:79], v[136:139], v[96:99], v[64:79]
	v_mfma_f32_32x32x16_bf16 v[48:63], v[172:175], v[244:247], v[48:63]
	v_exp_f32_e32 v175, v88
	v_exp_f32_e32 v173, v89
	v_exp_f32_e32 v174, v90
	v_exp_f32_e32 v172, v91
	v_add_f32_e32 v88, v190, v206
	v_add_f32_e32 v89, v191, v207
	v_add_f32_e32 v90, v188, v204
	v_add_f32_e32 v91, v189, v205
	v_mfma_f32_32x32x16_bf16 v[64:79], v[128:131], v[124:127], v[64:79]
	v_mfma_f32_32x32x16_bf16 v[48:63], v[176:179], v[248:251], v[48:63]
	v_exp_f32_e32 v179, v84
	v_exp_f32_e32 v177, v85
	v_exp_f32_e32 v178, v86
	v_exp_f32_e32 v176, v87
	v_add_f32_e32 v84, v194, v210
	v_add_f32_e32 v85, v195, v211
	v_add_f32_e32 v86, v192, v208
	v_add_f32_e32 v87, v193, v209
	v_add_f32_e32 v80, v84, v80
	v_add_f32_e32 v81, v85, v81
	v_mfma_f32_32x32x16_bf16 v[64:79], v[132:135], v[120:123], v[64:79]
	v_add_f32_e64 v82, v86, v82
	v_add_f32_e64 v83, v87, v83
	v_add_f32_e64 v80, v88, v80
	v_add_f32_e64 v81, v89, v81
	v_add_f32_e64 v82, v90, v82
	v_add_f32_e64 v83, v91, v83
	v_add_f32_e32 v80, v92, v80
	v_add_f32_e32 v81, v93, v81
	v_add_f32_e32 v82, v94, v82
	v_add_f32_e32 v83, v95, v83
	s_nop 0
	v_add_f32_e32 v80, v82, v80
	v_add_f32_e32 v81, v83, v81
	s_nop 0
	v_add_f32_e32 v80, v80, v81
	v_add_f32_e32 v230, v140, v80
	s_cbranch_scc0 .LBB0_529
	s_cmp_lg_u32 0, -1
	s_cselect_b32 s0, 0, 0
	s_add_i32 s0, s0, s52
	v_lshl_add_u64 v[80:81], v[166:167], 0, s[38:39]
	s_add_i32 s1, s0, 0x4000
	s_mov_b32 s44, m0
	s_mov_b32 m0, s1
	s_nop 0
	global_load_lds_dwordx4 v[80:81], off
	s_mov_b32 m0, s44
	v_lshl_add_u64 v[80:81], v[166:167], 0, s[40:41]
	s_addk_i32 s0, 0x4400
	s_mov_b32 s1, m0
	s_mov_b32 m0, s0
	s_nop 0
	global_load_lds_dwordx4 v[80:81], off
	s_mov_b32 m0, s1
	ds_read_b128 v[80:83], v231 offset:49152
	ds_read_b128 v[144:147], v231 offset:57344
	ds_read_b128 v[120:123], v232 offset:49152
	ds_read_b128 v[148:151], v232 offset:57344
	s_waitcnt lgkmcnt(3)
	v_mfma_f32_32x32x16_bf16 v[80:95], v[80:83], v[116:119], 0
	s_waitcnt lgkmcnt(1)
	v_mfma_f32_32x32x16_bf16 v[80:95], v[120:123], v[112:115], v[80:95]
	ds_read_b128 v[120:123], v233 offset:49152
	ds_read_b128 v[152:155], v233 offset:57344
	s_waitcnt lgkmcnt(1)
	v_mfma_f32_32x32x16_bf16 v[80:95], v[120:123], v[108:111], v[80:95]
	ds_read_b128 v[120:123], v234 offset:49152
	ds_read_b128 v[156:159], v234 offset:57344
	s_waitcnt lgkmcnt(1)
	v_mfma_f32_32x32x16_bf16 v[80:95], v[120:123], v[104:107], v[80:95]
	ds_read_b128 v[120:123], v235 offset:49152
	ds_read_b128 v[140:143], v235 offset:57344
	s_waitcnt lgkmcnt(1)
	v_mfma_f32_32x32x16_bf16 v[80:95], v[120:123], v[100:103], v[80:95]
	ds_read_b128 v[120:123], v236 offset:49152
	ds_read_b128 v[136:139], v236 offset:57344
	s_waitcnt lgkmcnt(1)
	v_mfma_f32_32x32x16_bf16 v[80:95], v[120:123], v[96:99], v[80:95]
	ds_read_b128 v[128:131], v237 offset:49152
	ds_read_b128 v[124:127], v229
	ds_read_b128 v[132:135], v237 offset:57344
	ds_read_b128 v[120:123], v229 offset:1024
	s_waitcnt lgkmcnt(2)
	v_mfma_f32_32x32x16_bf16 v[80:95], v[128:131], v[124:127], v[80:95]
	ds_read_b128 v[162:165], v238 offset:49152
	ds_read_b128 v[128:131], v238 offset:57344
	s_waitcnt lgkmcnt(1)
	v_mfma_f32_32x32x16_bf16 v[80:95], v[162:165], v[120:123], v[80:95]
	v_exp_f32_e32 v163, v66
	v_exp_f32_e32 v164, v67
	v_exp_f32_e32 v167, v70
	v_exp_f32_e32 v184, v71
	v_exp_f32_e32 v187, v74
	v_exp_f32_e32 v160, v64
	v_exp_f32_e32 v188, v75
	v_add_f32_e32 v64, v182, v163
	v_exp_f32_e32 v162, v65
	v_exp_f32_e32 v191, v78
	v_add_f32_e32 v64, 0, v64
	v_add_f32_e32 v65, v180, v164
	v_add_f32_e32 v66, v178, v167
	v_exp_f32_e32 v79, v79
	v_add_f32_e32 v65, 0, v65
	v_add_f32_e32 v64, v66, v64
	v_add_f32_e32 v66, v176, v184
	v_add_f32_e32 v65, v66, v65
	v_add_f32_e32 v66, v174, v187
	v_exp_f32_e32 v165, v68
	v_exp_f32_e32 v166, v69
	v_exp_f32_e32 v185, v72
	v_exp_f32_e32 v186, v73
	v_exp_f32_e32 v189, v76
	v_exp_f32_e32 v190, v77
	v_add_f32_e32 v64, v66, v64
	v_add_f32_e32 v66, v172, v188
	v_add_f32_e32 v65, v66, v65
	v_add_f32_e32 v66, v170, v191
	v_add_f32_e32 v64, v66, v64
	v_add_f32_e32 v66, v168, v79
	v_add_f32_e32 v65, v66, v65
	v_add_f32_e32 v192, v183, v160
	v_add_f32_e32 v193, v181, v162
	v_add_f32_e32 v194, v179, v165
	v_add_f32_e32 v195, v177, v166
	v_add_f32_e32 v196, v175, v185
	v_add_f32_e32 v197, v173, v186
	v_add_f32_e32 v198, v171, v189
	v_add_f32_e32 v199, v169, v190
	v_add_f32_e32 v200, v65, v64
	v_cvt_pk_bf16_f32 v64, v183, v181
	v_cvt_pk_bf16_f32 v65, v182, v180
	v_cvt_pk_bf16_f32 v66, v179, v177
	v_cvt_pk_bf16_f32 v67, v178, v176
	v_cvt_pk_bf16_f32 v68, v175, v173
	v_cvt_pk_bf16_f32 v69, v174, v172
	v_cvt_pk_bf16_f32 v70, v171, v169
	v_cvt_pk_bf16_f32 v71, v170, v168
	s_nop 0
	v_permlane32_swap_b32_e32 v64, v66
	v_permlane32_swap_b32_e32 v65, v67
	v_permlane32_swap_b32_e32 v68, v70
	v_permlane32_swap_b32_e32 v69, v71
	v_cvt_pk_bf16_f32 v72, v160, v162
	v_cvt_pk_bf16_f32 v73, v163, v164
	v_cvt_pk_bf16_f32 v74, v165, v166
	v_cvt_pk_bf16_f32 v75, v167, v184
	v_cvt_pk_bf16_f32 v76, v185, v186
	v_cvt_pk_bf16_f32 v77, v187, v188
	v_cvt_pk_bf16_f32 v78, v189, v190
	v_cvt_pk_bf16_f32 v79, v191, v79
	s_nop 0
	v_permlane32_swap_b32_e32 v72, v74
	v_permlane32_swap_b32_e32 v73, v75
	v_permlane32_swap_b32_e32 v76, v78
	v_permlane32_swap_b32_e32 v77, v79
	ds_read_b64_tr_b16 v[162:163], v228 offset:0
	ds_read_b64_tr_b16 v[164:165], v228 offset:0x800
	ds_read_b64_tr_b16 v[166:167], v228 offset:0x1000
	ds_read_b64_tr_b16 v[168:169], v228 offset:0x1800
	ds_read_b64_tr_b16 v[170:171], v228 offset:0x2000
	ds_read_b64_tr_b16 v[172:173], v228 offset:0x2800
	ds_read_b64_tr_b16 v[174:175], v228 offset:0x3000
	ds_read_b64_tr_b16 v[176:177], v228 offset:0x3800
	s_waitcnt lgkmcnt(0)
; #define WBAR0() do { asm volatile("s_waitcnt vmcnt(0)" ::: "memory"); __syncthreads(); } while (0)
; #define EXPH(P) do { _Pragma("unroll") for (int r = 0; r < 16; ++r) P[r] = __builtin_amdgcn_exp2f(P[r]); } while (0)
;     ...
;     pv_d0(o, vb0, pa0, pa1, pa2, pa3);
;     if (!isY) { EXPH(pB0); }
;     WBAR0();
	s_nop 0
	v_mfma_f32_32x32x16_bf16 v[0:15], v[64:67], v[162:165], v[0:15]
	ds_read_b64_tr_b16 v[162:163], v228 offset:0x200
	ds_read_b64_tr_b16 v[164:165], v228 offset:0xa00
	v_mfma_f32_32x32x16_bf16 v[0:15], v[68:71], v[166:169], v[0:15]
	ds_read_b64_tr_b16 v[166:167], v228 offset:0x1200
	ds_read_b64_tr_b16 v[168:169], v228 offset:0x1a00
	v_mfma_f32_32x32x16_bf16 v[0:15], v[72:75], v[170:173], v[0:15]
	ds_read_b64_tr_b16 v[170:171], v228 offset:0x2200
	ds_read_b64_tr_b16 v[172:173], v228 offset:0x2a00
	ds_read_b64_tr_b16 v[178:179], v228 offset:0x3200
	ds_read_b64_tr_b16 v[180:181], v228 offset:0x3a00
	s_waitcnt lgkmcnt(0)
	v_mfma_f32_32x32x16_bf16 v[0:15], v[76:79], v[174:177], v[0:15]
	v_mfma_f32_32x32x16_bf16 v[16:31], v[64:67], v[162:165], v[16:31]
	ds_read_b64_tr_b16 v[162:163], v228 offset:0x400
	ds_read_b64_tr_b16 v[164:165], v228 offset:0xc00
	v_mfma_f32_32x32x16_bf16 v[16:31], v[68:71], v[166:169], v[16:31]
	ds_read_b64_tr_b16 v[166:167], v228 offset:0x1400
	ds_read_b64_tr_b16 v[168:169], v228 offset:0x1c00
	v_mfma_f32_32x32x16_bf16 v[16:31], v[72:75], v[170:173], v[16:31]
	ds_read_b64_tr_b16 v[170:171], v228 offset:0x2400
	ds_read_b64_tr_b16 v[172:173], v228 offset:0x2c00
	ds_read_b64_tr_b16 v[174:175], v228 offset:0x3400
	ds_read_b64_tr_b16 v[176:177], v228 offset:0x3c00
	s_waitcnt lgkmcnt(0)
	v_mfma_f32_32x32x16_bf16 v[16:31], v[76:79], v[178:181], v[16:31]
	v_mfma_f32_32x32x16_bf16 v[32:47], v[64:67], v[162:165], v[32:47]
	ds_read_b64_tr_b16 v[162:163], v228 offset:0x600
	ds_read_b64_tr_b16 v[164:165], v228 offset:0xe00
	v_mfma_f32_32x32x16_bf16 v[32:47], v[68:71], v[166:169], v[32:47]
	ds_read_b64_tr_b16 v[166:167], v228 offset:0x1600
	ds_read_b64_tr_b16 v[168:169], v228 offset:0x1e00
	v_mfma_f32_32x32x16_bf16 v[32:47], v[72:75], v[170:173], v[32:47]
	ds_read_b64_tr_b16 v[170:171], v228 offset:0x2600
	ds_read_b64_tr_b16 v[172:173], v228 offset:0x2e00
	ds_read_b64_tr_b16 v[178:179], v228 offset:0x3600
	ds_read_b64_tr_b16 v[180:181], v228 offset:0x3e00
	s_waitcnt lgkmcnt(0)
	v_mfma_f32_32x32x16_bf16 v[32:47], v[76:79], v[174:177], v[32:47]
	v_mfma_f32_32x32x16_bf16 v[48:63], v[64:67], v[162:165], v[48:63]
	s_waitcnt vmcnt(0)
	v_exp_f32_e32 v80, v80
	v_exp_f32_e32 v81, v81
	v_exp_f32_e32 v82, v82
	v_exp_f32_e32 v83, v83
	v_exp_f32_e32 v84, v84
	v_exp_f32_e32 v85, v85
	v_mfma_f32_32x32x16_bf16 v[48:63], v[68:71], v[166:169], v[48:63]
	v_exp_f32_e32 v86, v86
	v_exp_f32_e32 v87, v87
	v_exp_f32_e32 v88, v88
	v_exp_f32_e32 v89, v89
	v_exp_f32_e32 v90, v90
	v_exp_f32_e32 v91, v91
	v_exp_f32_e32 v92, v92
	v_mfma_f32_32x32x16_bf16 v[48:63], v[72:75], v[170:173], v[48:63]
	v_exp_f32_e32 v93, v93
	v_exp_f32_e32 v94, v94
	v_exp_f32_e32 v95, v95
	s_waitcnt lgkmcnt(0)
	s_barrier
; #define SBAR() __builtin_amdgcn_sched_barrier(0)
; #define EXPH(P) do { _Pragma("unroll") for (int r = 0; r < 16; ++r) P[r] = __builtin_amdgcn_exp2f(P[r]); } while (0)
;     ...
;     if (isY) { EXPH(pB0); }
;     SBAR(); finishSM<true>(pB0, pB1, dummy_a, l_reg, pa0, pa1, pa2, pa3); SBAR();
;     pv_d0(o, vb0 + SHM_V, pa0, pa1, pa2, pa3);
;     __builtin_amdgcn_s_setprio(0);
;     (void)dummy_m;
;     { auto rr = __builtin_amdgcn_permlane32_swap(__float_as_uint(l_reg), __float_as_uint(l_reg), false, false); l_reg = __uint_as_float(rr[0]) + __uint_as_float(rr[1]); }
;     {
;         int t2 = threadIdx.x; asm volatile("" : "+v"(t2));
;         const int wid2 = t2 >> 6, lane2 = t2 & 63, r32b = lane2 & 31, hib = lane2 >> 5;
;         float* li2 = (float*)(lds + OFF_WS) + wid2 * 64;
;         if (hib == 0) li2[r32b] = l_reg; asm volatile("s_waitcnt lgkmcnt(0)" ::: "memory");
	v_mfma_f32_32x32x16_bf16 v[48:63], v[76:79], v[178:181], v[48:63]
	v_mfma_f32_32x32x16_bf16 v[64:79], v[144:147], v[116:119], 0
	v_mfma_f32_32x32x16_bf16 v[64:79], v[148:151], v[112:115], v[64:79]
	v_mfma_f32_32x32x16_bf16 v[64:79], v[152:155], v[108:111], v[64:79]
	v_mfma_f32_32x32x16_bf16 v[64:79], v[156:159], v[104:107], v[64:79]
	v_mfma_f32_32x32x16_bf16 v[64:79], v[140:143], v[100:103], v[64:79]
	v_mfma_f32_32x32x16_bf16 v[64:79], v[136:139], v[96:99], v[64:79]
	v_add_f32_e32 v96, 0, v192
	v_add_f32_e32 v97, 0, v193
	v_add_f32_e32 v96, v194, v96
	v_add_f32_e32 v97, v195, v97
	v_add_f32_e32 v96, v196, v96
	v_add_f32_e32 v97, v197, v97
	v_add_f32_e32 v96, v198, v96
	v_mfma_f32_32x32x16_bf16 v[64:79], v[132:135], v[124:127], v[64:79]
	v_add_f32_e32 v97, v199, v97
	v_add_f32_e32 v96, v97, v96
	v_add_f32_e32 v96, v200, v96
	v_add_f32_e32 v96, v230, v96
	v_mfma_f32_32x32x16_bf16 v[64:79], v[128:131], v[120:123], v[64:79]
	s_nop 11
	v_exp_f32_e32 v64, v64
	v_exp_f32_e32 v65, v65
	v_exp_f32_e32 v98, v68
	v_exp_f32_e32 v97, v66
	v_exp_f32_e32 v99, v69
	v_exp_f32_e32 v67, v67
	v_exp_f32_e32 v100, v70
	v_exp_f32_e32 v101, v71
	v_add_f32_e32 v66, v80, v64
	v_exp_f32_e32 v102, v72
	v_add_f32_e32 v66, 0, v66
	v_add_f32_e32 v68, v81, v65
	v_add_f32_e32 v71, v84, v98
	v_exp_f32_e32 v103, v73
	v_add_f32_e32 v68, 0, v68
	v_add_f32_e32 v69, v82, v97
	v_add_f32_e32 v66, v71, v66
	v_add_f32_e32 v71, v85, v99
	v_exp_f32_e32 v104, v74
	v_add_f32_e32 v69, 0, v69
	v_add_f32_e32 v70, v83, v67
	v_add_f32_e32 v68, v71, v68
	v_add_f32_e32 v71, v86, v100
	v_exp_f32_e32 v105, v75
	v_add_f32_e32 v70, 0, v70
	v_add_f32_e32 v69, v71, v69
	v_add_f32_e32 v71, v87, v101
	v_exp_f32_e32 v106, v76
	v_add_f32_e32 v70, v71, v70
	v_add_f32_e32 v71, v88, v102
	v_exp_f32_e32 v107, v77
	v_add_f32_e32 v66, v71, v66
	v_add_f32_e32 v71, v89, v103
	v_exp_f32_e32 v108, v78
	v_add_f32_e32 v68, v71, v68
	v_add_f32_e32 v71, v90, v104
	v_exp_f32_e32 v109, v79
	v_add_f32_e32 v69, v71, v69
	v_add_f32_e32 v71, v91, v105
	v_add_f32_e32 v70, v71, v70
	v_add_f32_e32 v71, v92, v106
	v_add_f32_e32 v66, v71, v66
	v_add_f32_e32 v71, v93, v107
	v_add_f32_e32 v68, v71, v68
	v_add_f32_e32 v71, v94, v108
	v_add_f32_e32 v69, v71, v69
	v_add_f32_e32 v71, v95, v109
	v_add_f32_e32 v70, v71, v70
	v_add_f32_e32 v66, v68, v66
	v_add_f32_e32 v68, v70, v69
	v_add_f32_e32 v66, v68, v66
	v_cvt_pk_bf16_f32 v68, v80, v81
	v_cvt_pk_bf16_f32 v69, v82, v83
	v_cvt_pk_bf16_f32 v70, v84, v85
	v_cvt_pk_bf16_f32 v71, v86, v87
	v_add_f32_e32 v66, v96, v66
	v_permlane32_swap_b32_e32 v68, v70
	v_permlane32_swap_b32_e32 v69, v71
	v_cvt_pk_bf16_f32 v72, v88, v89
	v_cvt_pk_bf16_f32 v73, v90, v91
	v_cvt_pk_bf16_f32 v74, v92, v93
	v_cvt_pk_bf16_f32 v75, v94, v95
	v_cvt_pk_bf16_f32 v76, v64, v65
	v_cvt_pk_bf16_f32 v77, v97, v67
	v_cvt_pk_bf16_f32 v78, v98, v99
	v_cvt_pk_bf16_f32 v79, v100, v101
	v_cvt_pk_bf16_f32 v80, v102, v103
	v_cvt_pk_bf16_f32 v81, v104, v105
	v_cvt_pk_bf16_f32 v82, v106, v107
	v_cvt_pk_bf16_f32 v83, v108, v109
	s_nop 0
	v_permlane32_swap_b32_e32 v72, v74
	v_permlane32_swap_b32_e32 v73, v75
	v_permlane32_swap_b32_e32 v76, v78
	v_permlane32_swap_b32_e32 v77, v79
	v_permlane32_swap_b32_e32 v80, v82
	v_permlane32_swap_b32_e32 v81, v83
	ds_read_b64_tr_b16 v[84:85], v227 offset:0
	ds_read_b64_tr_b16 v[86:87], v227 offset:0x800
	ds_read_b64_tr_b16 v[88:89], v227 offset:0x1000
	ds_read_b64_tr_b16 v[90:91], v227 offset:0x1800
	ds_read_b64_tr_b16 v[92:93], v227 offset:0x2000
	ds_read_b64_tr_b16 v[94:95], v227 offset:0x2800
	ds_read_b64_tr_b16 v[96:97], v227 offset:0x3000
	ds_read_b64_tr_b16 v[98:99], v227 offset:0x3800
	s_waitcnt lgkmcnt(0)
	s_nop 0
	v_mfma_f32_32x32x16_bf16 v[0:15], v[68:71], v[84:87], v[0:15]
	ds_read_b64_tr_b16 v[84:85], v227 offset:0x200
	ds_read_b64_tr_b16 v[86:87], v227 offset:0xa00
	v_mfma_f32_32x32x16_bf16 v[0:15], v[72:75], v[88:91], v[0:15]
	ds_read_b64_tr_b16 v[88:89], v227 offset:0x1200
	ds_read_b64_tr_b16 v[90:91], v227 offset:0x1a00
	v_mfma_f32_32x32x16_bf16 v[0:15], v[76:79], v[92:95], v[0:15]
	ds_read_b64_tr_b16 v[92:93], v227 offset:0x2200
	ds_read_b64_tr_b16 v[94:95], v227 offset:0x2a00
	ds_read_b64_tr_b16 v[100:101], v227 offset:0x3200
	ds_read_b64_tr_b16 v[102:103], v227 offset:0x3a00
	s_waitcnt lgkmcnt(0)
	v_mfma_f32_32x32x16_bf16 v[0:15], v[80:83], v[96:99], v[0:15]
	v_mfma_f32_32x32x16_bf16 v[16:31], v[68:71], v[84:87], v[16:31]
	ds_read_b64_tr_b16 v[84:85], v227 offset:0x400
	ds_read_b64_tr_b16 v[86:87], v227 offset:0xc00
	v_mfma_f32_32x32x16_bf16 v[16:31], v[72:75], v[88:91], v[16:31]
	ds_read_b64_tr_b16 v[88:89], v227 offset:0x1400
	ds_read_b64_tr_b16 v[90:91], v227 offset:0x1c00
	v_mfma_f32_32x32x16_bf16 v[16:31], v[76:79], v[92:95], v[16:31]
	ds_read_b64_tr_b16 v[92:93], v227 offset:0x2400
	ds_read_b64_tr_b16 v[94:95], v227 offset:0x2c00
	ds_read_b64_tr_b16 v[96:97], v227 offset:0x3400
	ds_read_b64_tr_b16 v[98:99], v227 offset:0x3c00
	s_waitcnt lgkmcnt(0)
	v_mfma_f32_32x32x16_bf16 v[16:31], v[80:83], v[100:103], v[16:31]
	v_mfma_f32_32x32x16_bf16 v[32:47], v[68:71], v[84:87], v[32:47]
	ds_read_b64_tr_b16 v[84:85], v227 offset:0x600
	ds_read_b64_tr_b16 v[86:87], v227 offset:0xe00
	v_mfma_f32_32x32x16_bf16 v[32:47], v[72:75], v[88:91], v[32:47]
	ds_read_b64_tr_b16 v[88:89], v227 offset:0x1600
	ds_read_b64_tr_b16 v[90:91], v227 offset:0x1e00
	v_mfma_f32_32x32x16_bf16 v[32:47], v[76:79], v[92:95], v[32:47]
	ds_read_b64_tr_b16 v[92:93], v227 offset:0x2600
	ds_read_b64_tr_b16 v[94:95], v227 offset:0x2e00
	ds_read_b64_tr_b16 v[100:101], v227 offset:0x3600
	ds_read_b64_tr_b16 v[102:103], v227 offset:0x3e00
	s_waitcnt lgkmcnt(0)
	v_mfma_f32_32x32x16_bf16 v[32:47], v[80:83], v[96:99], v[32:47]
	v_mfma_f32_32x32x16_bf16 v[48:63], v[68:71], v[84:87], v[48:63]
	v_mfma_f32_32x32x16_bf16 v[48:63], v[72:75], v[88:91], v[48:63]
	v_mfma_f32_32x32x16_bf16 v[48:63], v[76:79], v[92:95], v[48:63]
	v_mfma_f32_32x32x16_bf16 v[48:63], v[80:83], v[100:103], v[48:63]
	s_setprio 0
	v_mov_b32_e32 v64, v218
	v_mov_b32_e32 v69, v66
	s_nop 1
	v_permlane32_swap_b32_e32 v66, v69
	v_and_b32_e32 v65, 63, v64
	v_and_b32_e32 v68, 0x3fffffc0, v64
	v_and_b32_e32 v67, 31, v64
	v_lshl_add_u32 v68, v68, 2, s50
	v_cmp_gt_u32_e32 vcc, 32, v65
	s_and_saveexec_b64 s[0:1], vcc
	s_cbranch_execz .LBB0_525
	v_add_f32_e32 v66, v66, v69
	v_lshl_add_u32 v69, v67, 2, v68
	ds_write_b32 v69, v66
	s_branch .LBB0_525

; #define SBAR() __builtin_amdgcn_sched_barrier(0)
; #define DMA_K(t, buf) do { const char* kb_ = (const char*)Kh + (size_t)(t) * TILEB; \
;         glds16(kb_ + ksrc[0], (unsigned)__builtin_amdgcn_readfirstlane(lds0 + OFF_K + (buf) * SHM_K + (DQK == 128 ? widu * 2048 : widu * 1024))); \
;         if (DQK == 128) glds16(kb_ + ksrc[1], (unsigned)__builtin_amdgcn_readfirstlane(lds0 + OFF_K + (buf) * SHM_K + widu * 2048 + 1024)); } while (0)
; #define DMA_V(t, buf) do { const char* vb_ = (const char*)Vh + (size_t)(t) * TILEB; \
;         glds16(vb_ + vsrc[0], (unsigned)__builtin_amdgcn_readfirstlane(lds0 + (buf) * SHM_V + widu * 2048)); \
;         glds16(vb_ + vsrc[1], (unsigned)__builtin_amdgcn_readfirstlane(lds0 + (buf) * SHM_V + widu * 2048 + 1024)); } while (0)
; #define WBAR0() do { asm volatile("s_waitcnt vmcnt(0)" ::: "memory"); __syncthreads(); } while (0)
; template <bool FAST> __device__ __forceinline__ void finishSM(f32x16& p0, f32x16& p1, float alpha, float& l_reg, bf16x8& pa0, bf16x8& pa1, bf16x8& pa2, bf16x8& pa3) {
;     if (FAST) SBAR();
; #pragma unroll
;     for (int r = 0; r < 16; ++r) p1[r] = __builtin_amdgcn_exp2f(p1[r]);
;     float ps = 0;
;     if (FAST) { float s0 = 0.f, s1 = 0.f, s2 = 0.f, s3 = 0.f;
; #pragma unroll
;         for (int r = 0; r < 16; r += 4) { s0 += p0[r] + p1[r]; s1 += p0[r + 1] + p1[r + 1]; s2 += p0[r + 2] + p1[r + 2]; s3 += p0[r + 3] + p1[r + 3]; }
;         ps = (s0 + s1) + (s2 + s3); }
;     else {
; #pragma unroll
;     for (int r = 0; r < 16; ++r) ps += p0[r];
; #pragma unroll
;     for (int r = 0; r < 16; ++r) ps += p1[r];
;     }
;     if (FAST) { SBAR(); l_reg += ps; }
;     else { auto rr = __builtin_amdgcn_permlane32_swap(__float_as_uint(ps), __float_as_uint(ps), false, false);
;            ps = __uint_as_float(rr[0]) + __uint_as_float(rr[1]); l_reg = l_reg * alpha + ps; }
;     ...
;     PK4(p0, 0, pa0); PK4(p0, 8, pa1); PK4(p1, 0, pa2); PK4(p1, 8, pa3);
;     ...
; }
;     ...
;     for (int k = 1; k + 1 < NT; k += 2) {
;         DMA_K(k + 1, 0); DMA_V(k, 1); SBAR();
;         if (isY) { EXPH(pA0); }
;         SBAR(); qkt_mix<DQK, NREG>(pB0, pB1, K_lds + SHM_K, qr, qs, r32, hi);
;         finishSM<true>(pA0, pA1, dummy_a, l_reg, pa0, pa1, pa2, pa3); SBAR();
;         pv_d0(o, vb0, pa0, pa1, pa2, pa3);
;         if (!isY) { EXPH(pB0); }
;         WBAR0();
.LBB0_561:
	v_lshl_add_u64 v[80:81], v[152:153], 0, s[22:23]
	s_mov_b32 s0, m0
	s_mov_b32 m0, s55
	s_nop 0
	global_load_lds_dwordx4 v[80:81], off
	s_mov_b32 m0, s0
	s_cmp_lg_u32 0, -1
	s_cselect_b32 s0, 0, 0
	s_add_i32 s0, s0, s73
	v_lshl_add_u64 v[186:187], s[48:49], 0, v[132:133]
	s_add_i32 s1, s0, 0x4000
	s_mov_b32 s77, m0
	s_mov_b32 m0, s1
	s_nop 0
	global_load_lds_dwordx4 v[186:187], off
	s_mov_b32 m0, s77
	v_lshl_add_u64 v[80:81], v[186:187], 0, s[20:21]
	s_addk_i32 s0, 0x4400
	s_mov_b32 s1, m0
	s_mov_b32 m0, s0
	s_nop 0
	global_load_lds_dwordx4 v[80:81], off
	s_mov_b32 m0, s1
	ds_read_b128 v[80:83], v205 offset:40960
	ds_read_b128 v[124:127], v205 offset:45056
	ds_read_b128 v[112:115], v206 offset:40960
	ds_read_b128 v[120:123], v206 offset:45056
	s_waitcnt lgkmcnt(3)
	v_mfma_f32_32x32x16_bf16 v[80:95], v[80:83], v[108:111], 0
	s_waitcnt lgkmcnt(1)
	v_mfma_f32_32x32x16_bf16 v[80:95], v[112:115], v[104:107], v[80:95]
	ds_read_b128 v[112:115], v207 offset:40960
	ds_read_b128 v[116:119], v207 offset:45056
	s_waitcnt lgkmcnt(1)
	v_mfma_f32_32x32x16_bf16 v[80:95], v[112:115], v[100:103], v[80:95]
	ds_read_b128 v[172:175], v208 offset:40960
	ds_read_b128 v[112:115], v208 offset:45056
	s_waitcnt lgkmcnt(1)
	v_mfma_f32_32x32x16_bf16 v[80:95], v[172:175], v[96:99], v[80:95]
	v_exp_f32_e32 v199, v64
	v_exp_f32_e32 v197, v65
	v_exp_f32_e32 v198, v66
	v_exp_f32_e32 v196, v67
	v_exp_f32_e32 v67, v69
	v_exp_f32_e32 v66, v71
	v_exp_f32_e32 v65, v72
	v_exp_f32_e32 v64, v74
	v_exp_f32_e32 v195, v68
	v_exp_f32_e32 v194, v70
	v_exp_f32_e32 v193, v73
	v_exp_f32_e32 v192, v75
	v_exp_f32_e32 v191, v76
	v_exp_f32_e32 v189, v77
	v_exp_f32_e32 v190, v78
	v_exp_f32_e32 v188, v79
	v_cvt_pk_bf16_f32 v68, v171, v169
	v_cvt_pk_bf16_f32 v69, v170, v168
	v_cvt_pk_bf16_f32 v70, v167, v165
	v_cvt_pk_bf16_f32 v71, v166, v164
	v_cvt_pk_bf16_f32 v72, v163, v161
	v_cvt_pk_bf16_f32 v73, v162, v160
	v_cvt_pk_bf16_f32 v74, v159, v157
	v_cvt_pk_bf16_f32 v75, v158, v156
	v_cvt_pk_bf16_f32 v76, v199, v197
	v_cvt_pk_bf16_f32 v77, v198, v196
	v_cvt_pk_bf16_f32 v78, v195, v67
	v_cvt_pk_bf16_f32 v79, v194, v66
	s_nop 0
	v_permlane32_swap_b32_e32 v68, v70
	v_permlane32_swap_b32_e32 v69, v71
	v_permlane32_swap_b32_e32 v72, v74
	v_permlane32_swap_b32_e32 v73, v75
	v_permlane32_swap_b32_e32 v76, v78
	v_permlane32_swap_b32_e32 v77, v79
	v_cvt_pk_bf16_f32 v210, v65, v193
	v_cvt_pk_bf16_f32 v211, v64, v192
	v_cvt_pk_bf16_f32 v212, v191, v189
	v_cvt_pk_bf16_f32 v213, v190, v188
	s_nop 0
	v_permlane32_swap_b32_e32 v210, v212
	v_permlane32_swap_b32_e32 v211, v213
	ds_read_b64_tr_b16 v[172:173], v203 offset:0
	ds_read_b64_tr_b16 v[174:175], v203 offset:0x800
	ds_read_b64_tr_b16 v[176:177], v203 offset:0x1000
	ds_read_b64_tr_b16 v[178:179], v203 offset:0x1800
	ds_read_b64_tr_b16 v[180:181], v203 offset:0x2000
	ds_read_b64_tr_b16 v[182:183], v203 offset:0x2800
	ds_read_b64_tr_b16 v[214:215], v203 offset:0x3000
	ds_read_b64_tr_b16 v[216:217], v203 offset:0x3800
	s_waitcnt lgkmcnt(0)
	s_nop 0
	v_mfma_f32_32x32x16_bf16 v[0:15], v[68:71], v[172:175], v[0:15]
	ds_read_b64_tr_b16 v[172:173], v203 offset:0x200
	ds_read_b64_tr_b16 v[174:175], v203 offset:0xa00
	v_mfma_f32_32x32x16_bf16 v[0:15], v[72:75], v[176:179], v[0:15]
	ds_read_b64_tr_b16 v[176:177], v203 offset:0x1200
	ds_read_b64_tr_b16 v[178:179], v203 offset:0x1a00
	v_mfma_f32_32x32x16_bf16 v[0:15], v[76:79], v[180:183], v[0:15]
	ds_read_b64_tr_b16 v[180:181], v203 offset:0x2200
	ds_read_b64_tr_b16 v[182:183], v203 offset:0x2a00
	ds_read_b64_tr_b16 v[224:225], v203 offset:0x3200
	ds_read_b64_tr_b16 v[226:227], v203 offset:0x3a00
	s_waitcnt lgkmcnt(0)
	v_mfma_f32_32x32x16_bf16 v[0:15], v[210:213], v[214:217], v[0:15]
	v_mfma_f32_32x32x16_bf16 v[16:31], v[68:71], v[172:175], v[16:31]
	ds_read_b64_tr_b16 v[172:173], v203 offset:0x400
	ds_read_b64_tr_b16 v[174:175], v203 offset:0xc00
	v_mfma_f32_32x32x16_bf16 v[16:31], v[72:75], v[176:179], v[16:31]
	ds_read_b64_tr_b16 v[176:177], v203 offset:0x1400
	ds_read_b64_tr_b16 v[178:179], v203 offset:0x1c00
	v_mfma_f32_32x32x16_bf16 v[16:31], v[76:79], v[180:183], v[16:31]
	ds_read_b64_tr_b16 v[180:181], v203 offset:0x2400
	ds_read_b64_tr_b16 v[182:183], v203 offset:0x2c00
	ds_read_b64_tr_b16 v[214:215], v203 offset:0x3400
	ds_read_b64_tr_b16 v[216:217], v203 offset:0x3c00
	s_waitcnt lgkmcnt(0)
	v_mfma_f32_32x32x16_bf16 v[16:31], v[210:213], v[224:227], v[16:31]
	v_mfma_f32_32x32x16_bf16 v[32:47], v[68:71], v[172:175], v[32:47]
	ds_read_b64_tr_b16 v[172:173], v203 offset:0x600
	ds_read_b64_tr_b16 v[174:175], v203 offset:0xe00
	v_mfma_f32_32x32x16_bf16 v[32:47], v[72:75], v[176:179], v[32:47]
	ds_read_b64_tr_b16 v[176:177], v203 offset:0x1600
	ds_read_b64_tr_b16 v[178:179], v203 offset:0x1e00
	ds_read_b64_tr_b16 v[224:225], v203 offset:0x2600
	ds_read_b64_tr_b16 v[226:227], v203 offset:0x2e00
	ds_read_b64_tr_b16 v[228:229], v203 offset:0x3600
	ds_read_b64_tr_b16 v[230:231], v203 offset:0x3e00
	s_waitcnt lgkmcnt(0)
	v_mfma_f32_32x32x16_bf16 v[32:47], v[76:79], v[180:183], v[32:47]
	v_mfma_f32_32x32x16_bf16 v[32:47], v[210:213], v[214:217], v[32:47]
	v_mfma_f32_32x32x16_bf16 v[48:63], v[68:71], v[172:175], v[48:63]
	v_exp_f32_e32 v180, v86
	v_exp_f32_e32 v175, v89
	v_exp_f32_e32 v185, v80
	v_exp_f32_e32 v183, v81
	v_exp_f32_e32 v184, v82
	v_exp_f32_e32 v182, v83
	v_add_f32_e32 v80, v170, v198
	v_add_f32_e32 v81, v171, v199
	v_mfma_f32_32x32x16_bf16 v[48:63], v[72:75], v[176:179], v[48:63]
	v_exp_f32_e32 v178, v87
	v_exp_f32_e32 v177, v88
	v_add_f32_e32 v86, v164, v66
	v_add_f32_e32 v87, v165, v67
	v_add_f32_e32 v88, v162, v64
	v_add_f32_e32 v89, v163, v65
	v_add_f32_e32 v82, v168, v196
	v_add_f32_e32 v83, v169, v197
	v_exp_f32_e32 v181, v84
	v_exp_f32_e32 v179, v85
	v_mfma_f32_32x32x16_bf16 v[48:63], v[76:79], v[224:227], v[48:63]
	v_add_f32_e64 v84, v166, v194
	v_add_f32_e64 v85, v167, v195
	v_exp_f32_e32 v176, v90
	v_exp_f32_e32 v174, v91
	v_add_f32_e32 v90, v160, v192
	v_add_f32_e32 v91, v161, v193
	v_add_f32_e32 v80, v84, v80
	v_add_f32_e32 v81, v85, v81
	v_mfma_f32_32x32x16_bf16 v[64:79], v[124:127], v[108:111], 0
	v_add_f32_e64 v82, v86, v82
	v_add_f32_e64 v83, v87, v83
	v_exp_f32_e32 v173, v92
	v_exp_f32_e32 v155, v93
	v_exp_f32_e32 v172, v94
	v_exp_f32_e32 v154, v95
	v_add_f32_e32 v92, v158, v190
	v_add_f32_e32 v93, v159, v191
	v_add_f32_e32 v94, v156, v188
	v_add_f32_e32 v95, v157, v189
	v_mfma_f32_32x32x16_bf16 v[64:79], v[120:123], v[104:107], v[64:79]
	v_add_f32_e64 v80, v88, v80
	v_add_f32_e64 v81, v89, v81
	v_add_f32_e64 v82, v90, v82
	v_add_f32_e64 v83, v91, v83
	v_add_f32_e64 v80, v92, v80
	v_add_f32_e64 v81, v93, v81
	v_add_f32_e32 v82, v94, v82
	v_add_f32_e32 v83, v95, v83
	s_waitcnt vmcnt(0)
	s_waitcnt lgkmcnt(0)
	v_add_f32_e32 v80, v82, v80
	v_add_f32_e32 v81, v83, v81
	v_mfma_f32_32x32x16_bf16 v[64:79], v[116:119], v[100:103], v[64:79]
	s_barrier
; #define SBAR() __builtin_amdgcn_sched_barrier(0)
; #define DMA_K(t, buf) do { const char* kb_ = (const char*)Kh + (size_t)(t) * TILEB; \
;         glds16(kb_ + ksrc[0], (unsigned)__builtin_amdgcn_readfirstlane(lds0 + OFF_K + (buf) * SHM_K + (DQK == 128 ? widu * 2048 : widu * 1024))); \
;         if (DQK == 128) glds16(kb_ + ksrc[1], (unsigned)__builtin_amdgcn_readfirstlane(lds0 + OFF_K + (buf) * SHM_K + widu * 2048 + 1024)); } while (0)
; #define DMA_V(t, buf) do { const char* vb_ = (const char*)Vh + (size_t)(t) * TILEB; \
;         glds16(vb_ + vsrc[0], (unsigned)__builtin_amdgcn_readfirstlane(lds0 + (buf) * SHM_V + widu * 2048)); \
;         glds16(vb_ + vsrc[1], (unsigned)__builtin_amdgcn_readfirstlane(lds0 + (buf) * SHM_V + widu * 2048 + 1024)); } while (0)
; #define EXPH(P) do { _Pragma("unroll") for (int r = 0; r < 16; ++r) P[r] = __builtin_amdgcn_exp2f(P[r]); } while (0)
;     ...
;         DMA_K(k + 2, 1); DMA_V(k + 1, 0); SBAR();
;         if (isY) { EXPH(pB0); }
;         SBAR(); qkt_mix<DQK, NREG>(pA0, pA1, K_lds, qr, qs, r32, hi);
;         finishSM<true>(pB0, pB1, dummy_a, l_reg, pa0, pa1, pa2, pa3); SBAR();
;         pv_d0(o, vb0 + SHM_V, pa0, pa1, pa2, pa3);
	s_mov_b32 s0, m0
	s_mov_b32 m0, s74
	s_nop 0
	global_load_lds_dwordx4 v[152:153], off
	s_mov_b32 m0, s0
	v_add_f32_e32 v141, v80, v81
	v_lshl_add_u64 v[80:81], v[186:187], 0, s[6:7]
	s_mov_b32 s0, m0
	s_mov_b32 m0, s75
	s_nop 0
	global_load_lds_dwordx4 v[80:81], off
	s_mov_b32 m0, s0
	v_lshl_add_u64 v[80:81], v[186:187], 0, s[26:27]
	v_mfma_f32_32x32x16_bf16 v[48:63], v[210:213], v[228:231], v[48:63]
	s_mov_b32 s0, m0
	s_mov_b32 m0, s76
	s_nop 0
	global_load_lds_dwordx4 v[80:81], off
	s_mov_b32 m0, s0
	v_mfma_f32_32x32x16_bf16 v[64:79], v[112:115], v[96:99], v[64:79]
	ds_read_b128 v[80:83], v205 offset:32768
	ds_read_b128 v[156:159], v205 offset:36864
	ds_read_b128 v[112:115], v206 offset:32768
	ds_read_b128 v[124:127], v206 offset:36864
	s_waitcnt lgkmcnt(3)
	v_mfma_f32_32x32x16_bf16 v[80:95], v[80:83], v[108:111], 0
	s_waitcnt lgkmcnt(1)
	v_mfma_f32_32x32x16_bf16 v[80:95], v[112:115], v[104:107], v[80:95]
	ds_read_b128 v[112:115], v207 offset:32768
	ds_read_b128 v[120:123], v207 offset:36864
	s_waitcnt lgkmcnt(1)
	v_mfma_f32_32x32x16_bf16 v[80:95], v[112:115], v[100:103], v[80:95]
	ds_read_b128 v[116:119], v208 offset:32768
	ds_read_b128 v[112:115], v208 offset:36864
	s_waitcnt lgkmcnt(1)
	v_mfma_f32_32x32x16_bf16 v[80:95], v[116:119], v[96:99], v[80:95]
	v_exp_f32_e32 v201, v64
	v_exp_f32_e32 v199, v65
	v_exp_f32_e32 v200, v66
	v_exp_f32_e32 v198, v67
	v_exp_f32_e32 v197, v68
	v_exp_f32_e32 v195, v69
	v_exp_f32_e32 v196, v70
	v_exp_f32_e32 v194, v71
	v_exp_f32_e32 v193, v72
	v_exp_f32_e32 v191, v73
	v_exp_f32_e32 v192, v74
	v_exp_f32_e32 v190, v75
	v_exp_f32_e32 v189, v76
	v_exp_f32_e32 v187, v77
	v_exp_f32_e32 v188, v78
	v_exp_f32_e32 v186, v79
	v_cvt_pk_bf16_f32 v64, v185, v183
	v_cvt_pk_bf16_f32 v65, v184, v182
	v_cvt_pk_bf16_f32 v66, v181, v179
	v_cvt_pk_bf16_f32 v67, v180, v178
	v_cvt_pk_bf16_f32 v160, v177, v175
	v_cvt_pk_bf16_f32 v161, v176, v174
	v_cvt_pk_bf16_f32 v162, v173, v155
	v_cvt_pk_bf16_f32 v163, v172, v154
	s_nop 0
	v_permlane32_swap_b32_e32 v64, v66
	v_permlane32_swap_b32_e32 v65, v67
	v_permlane32_swap_b32_e32 v160, v162
	v_permlane32_swap_b32_e32 v161, v163
	v_cvt_pk_bf16_f32 v210, v201, v199
	v_cvt_pk_bf16_f32 v211, v200, v198
	v_cvt_pk_bf16_f32 v212, v197, v195
	v_cvt_pk_bf16_f32 v213, v196, v194
	v_cvt_pk_bf16_f32 v116, v193, v191
	v_cvt_pk_bf16_f32 v117, v192, v190
	v_cvt_pk_bf16_f32 v118, v189, v187
	v_cvt_pk_bf16_f32 v119, v188, v186
	s_nop 0
	v_permlane32_swap_b32_e32 v210, v212
	v_permlane32_swap_b32_e32 v211, v213
	v_permlane32_swap_b32_e32 v116, v118
	v_permlane32_swap_b32_e32 v117, v119
	ds_read_b64_tr_b16 v[68:69], v204 offset:0
	ds_read_b64_tr_b16 v[70:71], v204 offset:0x800
	ds_read_b64_tr_b16 v[72:73], v204 offset:0x1000
	ds_read_b64_tr_b16 v[74:75], v204 offset:0x1800
	ds_read_b64_tr_b16 v[76:77], v204 offset:0x2000
	ds_read_b64_tr_b16 v[78:79], v204 offset:0x2800
	ds_read_b64_tr_b16 v[164:165], v204 offset:0x3000
	ds_read_b64_tr_b16 v[166:167], v204 offset:0x3800
	s_waitcnt lgkmcnt(0)
	s_nop 0
	v_mfma_f32_32x32x16_bf16 v[0:15], v[64:67], v[68:71], v[0:15]
	ds_read_b64_tr_b16 v[68:69], v204 offset:0x200
	ds_read_b64_tr_b16 v[70:71], v204 offset:0xa00
	v_mfma_f32_32x32x16_bf16 v[0:15], v[160:163], v[72:75], v[0:15]
	ds_read_b64_tr_b16 v[72:73], v204 offset:0x1200
	ds_read_b64_tr_b16 v[74:75], v204 offset:0x1a00
	v_mfma_f32_32x32x16_bf16 v[0:15], v[210:213], v[76:79], v[0:15]
	ds_read_b64_tr_b16 v[76:77], v204 offset:0x2200
	ds_read_b64_tr_b16 v[78:79], v204 offset:0x2a00
	ds_read_b64_tr_b16 v[168:169], v204 offset:0x3200
	ds_read_b64_tr_b16 v[170:171], v204 offset:0x3a00
	s_waitcnt lgkmcnt(0)
	v_mfma_f32_32x32x16_bf16 v[0:15], v[116:119], v[164:167], v[0:15]
	v_mfma_f32_32x32x16_bf16 v[16:31], v[64:67], v[68:71], v[16:31]
	ds_read_b64_tr_b16 v[68:69], v204 offset:0x400
	ds_read_b64_tr_b16 v[70:71], v204 offset:0xc00
	v_mfma_f32_32x32x16_bf16 v[16:31], v[160:163], v[72:75], v[16:31]
	ds_read_b64_tr_b16 v[72:73], v204 offset:0x1400
	ds_read_b64_tr_b16 v[74:75], v204 offset:0x1c00
	v_mfma_f32_32x32x16_bf16 v[16:31], v[210:213], v[76:79], v[16:31]
	ds_read_b64_tr_b16 v[76:77], v204 offset:0x2400
	ds_read_b64_tr_b16 v[78:79], v204 offset:0x2c00
	ds_read_b64_tr_b16 v[164:165], v204 offset:0x3400
	ds_read_b64_tr_b16 v[166:167], v204 offset:0x3c00
	s_waitcnt lgkmcnt(0)
	v_mfma_f32_32x32x16_bf16 v[16:31], v[116:119], v[168:171], v[16:31]
	v_mfma_f32_32x32x16_bf16 v[32:47], v[64:67], v[68:71], v[32:47]
	ds_read_b64_tr_b16 v[68:69], v204 offset:0x600
	ds_read_b64_tr_b16 v[70:71], v204 offset:0xe00
	ds_read_b64_tr_b16 v[214:215], v204 offset:0x1600
	ds_read_b64_tr_b16 v[216:217], v204 offset:0x1e00
	ds_read_b64_tr_b16 v[224:225], v204 offset:0x2600
	ds_read_b64_tr_b16 v[226:227], v204 offset:0x2e00
	ds_read_b64_tr_b16 v[228:229], v204 offset:0x3600
	v_mfma_f32_32x32x16_bf16 v[32:47], v[160:163], v[72:75], v[32:47]
	ds_read_b64_tr_b16 v[230:231], v204 offset:0x3e00
	s_waitcnt lgkmcnt(0)
; #define SBAR() __builtin_amdgcn_sched_barrier(0)
; #define DMA_V(t, buf) do { const char* vb_ = (const char*)Vh + (size_t)(t) * TILEB; \
;         glds16(vb_ + vsrc[0], (unsigned)__builtin_amdgcn_readfirstlane(lds0 + (buf) * SHM_V + widu * 2048)); \
;         glds16(vb_ + vsrc[1], (unsigned)__builtin_amdgcn_readfirstlane(lds0 + (buf) * SHM_V + widu * 2048 + 1024)); } while (0)
; #define WBAR0() do { asm volatile("s_waitcnt vmcnt(0)" ::: "memory"); __syncthreads(); } while (0)
; #define EXPH(P) do { _Pragma("unroll") for (int r = 0; r < 16; ++r) P[r] = __builtin_amdgcn_exp2f(P[r]); } while (0)
;     ...
;         if (!isY) { EXPH(pA0); }
;         WBAR0();
;     }
;     DMA_V(NT - 1, 1); SBAR();
;     if (isY) { EXPH(pA0); }
;     SBAR(); qkt_mix<DQK, NREG>(pB0, pB1, K_lds + SHM_K, qr, qs, r32, hi);
;     finishSM<true>(pA0, pA1, dummy_a, l_reg, pa0, pa1, pa2, pa3); SBAR();
;     pv_d0(o, vb0, pa0, pa1, pa2, pa3);
	v_mfma_f32_32x32x16_bf16 v[32:47], v[210:213], v[76:79], v[32:47]
	v_mfma_f32_32x32x16_bf16 v[32:47], v[116:119], v[164:167], v[32:47]
	v_mfma_f32_32x32x16_bf16 v[48:63], v[64:67], v[68:71], v[48:63]
	v_exp_f32_e32 v171, v80
	v_exp_f32_e32 v169, v81
	v_exp_f32_e32 v170, v82
	v_exp_f32_e32 v168, v83
	v_add_f32_e32 v80, v184, v200
	v_add_f32_e32 v81, v185, v201
	v_add_f32_e32 v82, v182, v198
	v_add_f32_e32 v83, v183, v199
	v_exp_f32_e32 v167, v84
	v_mfma_f32_32x32x16_bf16 v[64:79], v[156:159], v[108:111], 0
	v_exp_f32_e32 v165, v85
	v_exp_f32_e32 v166, v86
	v_exp_f32_e32 v164, v87
	v_add_f32_e32 v84, v180, v196
	v_add_f32_e32 v85, v181, v197
	v_add_f32_e32 v86, v178, v194
	v_add_f32_e32 v87, v179, v195
	v_mfma_f32_32x32x16_bf16 v[48:63], v[160:163], v[214:217], v[48:63]
	v_exp_f32_e32 v163, v88
	v_exp_f32_e32 v161, v89
	v_exp_f32_e32 v162, v90
	v_exp_f32_e32 v160, v91
	v_add_f32_e32 v88, v176, v192
	v_add_f32_e32 v89, v177, v193
	v_add_f32_e32 v90, v174, v190
	v_add_f32_e32 v91, v175, v191
	v_add_f32_e32 v80, v84, v80
	v_add_f32_e32 v81, v85, v81
	v_mfma_f32_32x32x16_bf16 v[64:79], v[124:127], v[104:107], v[64:79]
	v_add_f32_e64 v82, v86, v82
	v_add_f32_e64 v83, v87, v83
	v_exp_f32_e32 v159, v92
	v_exp_f32_e32 v157, v93
	v_exp_f32_e32 v158, v94
	v_exp_f32_e32 v156, v95
	v_add_f32_e32 v92, v172, v188
	v_add_f32_e32 v93, v173, v189
	v_add_f32_e32 v94, v154, v186
	v_add_f32_e32 v95, v155, v187
	v_mfma_f32_32x32x16_bf16 v[48:63], v[210:213], v[224:227], v[48:63]
	v_add_f32_e64 v80, v88, v80
	v_add_f32_e64 v81, v89, v81
	v_add_f32_e64 v82, v90, v82
	v_add_f32_e64 v83, v91, v83
	s_add_i32 s72, s72, 2
	v_add_f32_e32 v80, v92, v80
	v_add_f32_e32 v81, v93, v81
	v_add_f32_e32 v82, v94, v82
	v_add_f32_e32 v83, v95, v83
	s_waitcnt vmcnt(0)
	s_add_u32 s48, s48, 0xc0000
	v_mfma_f32_32x32x16_bf16 v[64:79], v[120:123], v[100:103], v[64:79]
	v_add_f32_e64 v80, v82, v80
	v_add_f32_e64 v81, v83, v81
	v_add_f32_e32 v124, v134, v141
	s_addc_u32 s49, s49, 0
	v_add_f32_e32 v80, v80, v81
	v_lshl_add_u64 v[152:153], v[152:153], 0, s[28:29]
	s_cmp_gt_u32 s72, 64
	v_add_f32_e32 v134, v124, v80
	v_mfma_f32_32x32x16_bf16 v[48:63], v[116:119], v[228:231], v[48:63]
	s_waitcnt lgkmcnt(0)
	s_barrier
	v_mfma_f32_32x32x16_bf16 v[64:79], v[112:115], v[96:99], v[64:79]
	s_cbranch_scc0 .LBB0_561
	s_cmp_lg_u32 0, -1
	s_cselect_b32 s0, 0, 0
	s_add_i32 s0, s0, s73
	v_lshl_add_u64 v[152:153], v[146:147], 0, s[38:39]
	s_add_i32 s1, s0, 0x4000
	s_mov_b32 s48, m0
	s_mov_b32 m0, s1
	s_nop 0
	global_load_lds_dwordx4 v[152:153], off
	s_mov_b32 m0, s48
	v_lshl_add_u64 v[154:155], v[146:147], 0, s[40:41]
	s_addk_i32 s0, 0x4400
	s_mov_b32 s1, m0
	s_mov_b32 m0, s0
	s_nop 0
	global_load_lds_dwordx4 v[154:155], off
	s_mov_b32 m0, s1
	ds_read_b128 v[80:83], v205 offset:40960
	ds_read_b128 v[124:127], v205 offset:45056
	ds_read_b128 v[112:115], v206 offset:40960
	ds_read_b128 v[120:123], v206 offset:45056
	s_waitcnt lgkmcnt(3)
	v_mfma_f32_32x32x16_bf16 v[80:95], v[80:83], v[108:111], 0
	s_waitcnt lgkmcnt(1)
	v_mfma_f32_32x32x16_bf16 v[80:95], v[112:115], v[104:107], v[80:95]
	ds_read_b128 v[112:115], v207 offset:40960
	ds_read_b128 v[116:119], v207 offset:45056
	s_waitcnt lgkmcnt(1)
	v_mfma_f32_32x32x16_bf16 v[80:95], v[112:115], v[100:103], v[80:95]
	ds_read_b128 v[172:175], v208 offset:40960
	ds_read_b128 v[112:115], v208 offset:45056
	s_waitcnt lgkmcnt(1)
	v_mfma_f32_32x32x16_bf16 v[80:95], v[172:175], v[96:99], v[80:95]
	v_exp_f32_e32 v173, v66
	v_exp_f32_e32 v174, v67
	v_exp_f32_e32 v177, v70
	v_exp_f32_e32 v178, v71
	v_exp_f32_e32 v181, v74
	v_exp_f32_e32 v141, v64
	v_exp_f32_e32 v182, v75
	v_add_f32_e32 v64, v170, v173
	v_exp_f32_e32 v172, v65
	v_exp_f32_e32 v185, v78
	v_add_f32_e32 v64, 0, v64
	v_add_f32_e32 v65, v168, v174
	v_add_f32_e32 v66, v166, v177
	v_exp_f32_e32 v79, v79
	v_add_f32_e32 v65, 0, v65
	v_add_f32_e32 v64, v66, v64
	v_add_f32_e32 v66, v164, v178
	v_add_f32_e32 v65, v66, v65
	v_add_f32_e32 v66, v162, v181
	v_exp_f32_e32 v175, v68
	v_exp_f32_e32 v176, v69
	v_exp_f32_e32 v179, v72
	v_exp_f32_e32 v180, v73
	v_exp_f32_e32 v183, v76
	v_exp_f32_e32 v184, v77
	v_add_f32_e32 v64, v66, v64
	v_add_f32_e32 v66, v160, v182
	v_add_f32_e32 v65, v66, v65
	v_add_f32_e32 v66, v158, v185
	v_add_f32_e32 v64, v66, v64
	v_add_f32_e32 v66, v156, v79
	v_add_f32_e32 v65, v66, v65
	v_add_f32_e32 v186, v171, v141
	v_add_f32_e32 v187, v169, v172
	v_add_f32_e32 v188, v167, v175
	v_add_f32_e32 v189, v165, v176
	v_add_f32_e32 v190, v163, v179
	v_add_f32_e32 v191, v161, v180
	v_add_f32_e32 v192, v159, v183
	v_add_f32_e32 v193, v157, v184
	v_add_f32_e32 v194, v65, v64
	v_cvt_pk_bf16_f32 v64, v171, v169
	v_cvt_pk_bf16_f32 v65, v170, v168
	v_cvt_pk_bf16_f32 v66, v167, v165
	v_cvt_pk_bf16_f32 v67, v166, v164
	v_cvt_pk_bf16_f32 v68, v163, v161
	v_cvt_pk_bf16_f32 v69, v162, v160
	v_cvt_pk_bf16_f32 v70, v159, v157
	v_cvt_pk_bf16_f32 v71, v158, v156
	s_nop 0
	v_permlane32_swap_b32_e32 v64, v66
	v_permlane32_swap_b32_e32 v65, v67
	v_permlane32_swap_b32_e32 v68, v70
	v_cvt_pk_bf16_f32 v72, v141, v172
	v_cvt_pk_bf16_f32 v73, v173, v174
	v_cvt_pk_bf16_f32 v74, v175, v176
	v_cvt_pk_bf16_f32 v75, v177, v178
	v_cvt_pk_bf16_f32 v76, v179, v180
	v_cvt_pk_bf16_f32 v77, v181, v182
	v_cvt_pk_bf16_f32 v78, v183, v184
	v_cvt_pk_bf16_f32 v79, v185, v79
	v_permlane32_swap_b32_e32 v69, v71
	v_permlane32_swap_b32_e32 v72, v74
	v_permlane32_swap_b32_e32 v73, v75
	v_permlane32_swap_b32_e32 v76, v78
	v_permlane32_swap_b32_e32 v77, v79
	ds_read_b64_tr_b16 v[156:157], v203 offset:0
	ds_read_b64_tr_b16 v[158:159], v203 offset:0x800
	ds_read_b64_tr_b16 v[160:161], v203 offset:0x1000
	ds_read_b64_tr_b16 v[162:163], v203 offset:0x1800
	ds_read_b64_tr_b16 v[164:165], v203 offset:0x2000
	ds_read_b64_tr_b16 v[166:167], v203 offset:0x2800
	ds_read_b64_tr_b16 v[168:169], v203 offset:0x3000
	ds_read_b64_tr_b16 v[170:171], v203 offset:0x3800
	s_waitcnt lgkmcnt(0)
; #define SBAR() __builtin_amdgcn_sched_barrier(0)
; #define WBAR0() do { asm volatile("s_waitcnt vmcnt(0)" ::: "memory"); __syncthreads(); } while (0)
; #define EXPH(P) do { _Pragma("unroll") for (int r = 0; r < 16; ++r) P[r] = __builtin_amdgcn_exp2f(P[r]); } while (0)
;     ...
;     pv_d0(o, vb0, pa0, pa1, pa2, pa3);
;     if (!isY) { EXPH(pB0); }
;     WBAR0();
;     if (isY) { EXPH(pB0); }
;     SBAR(); finishSM<true>(pB0, pB1, dummy_a, l_reg, pa0, pa1, pa2, pa3); SBAR();
;     pv_d0(o, vb0 + SHM_V, pa0, pa1, pa2, pa3);
	s_nop 0
	v_mfma_f32_32x32x16_bf16 v[0:15], v[64:67], v[156:159], v[0:15]
	ds_read_b64_tr_b16 v[156:157], v203 offset:0x200
	ds_read_b64_tr_b16 v[158:159], v203 offset:0xa00
	v_mfma_f32_32x32x16_bf16 v[0:15], v[68:71], v[160:163], v[0:15]
	ds_read_b64_tr_b16 v[160:161], v203 offset:0x1200
	ds_read_b64_tr_b16 v[162:163], v203 offset:0x1a00
	v_mfma_f32_32x32x16_bf16 v[0:15], v[72:75], v[164:167], v[0:15]
	ds_read_b64_tr_b16 v[164:165], v203 offset:0x2200
	ds_read_b64_tr_b16 v[166:167], v203 offset:0x2a00
	ds_read_b64_tr_b16 v[172:173], v203 offset:0x3200
	ds_read_b64_tr_b16 v[174:175], v203 offset:0x3a00
	s_waitcnt lgkmcnt(0)
	v_mfma_f32_32x32x16_bf16 v[0:15], v[76:79], v[168:171], v[0:15]
	v_mfma_f32_32x32x16_bf16 v[16:31], v[64:67], v[156:159], v[16:31]
	ds_read_b64_tr_b16 v[156:157], v203 offset:0x400
	ds_read_b64_tr_b16 v[158:159], v203 offset:0xc00
	v_mfma_f32_32x32x16_bf16 v[16:31], v[68:71], v[160:163], v[16:31]
	ds_read_b64_tr_b16 v[160:161], v203 offset:0x1400
	ds_read_b64_tr_b16 v[162:163], v203 offset:0x1c00
	v_mfma_f32_32x32x16_bf16 v[16:31], v[72:75], v[164:167], v[16:31]
	ds_read_b64_tr_b16 v[164:165], v203 offset:0x2400
	ds_read_b64_tr_b16 v[166:167], v203 offset:0x2c00
	ds_read_b64_tr_b16 v[168:169], v203 offset:0x3400
	ds_read_b64_tr_b16 v[170:171], v203 offset:0x3c00
	s_waitcnt lgkmcnt(0)
	v_mfma_f32_32x32x16_bf16 v[16:31], v[76:79], v[172:175], v[16:31]
	v_mfma_f32_32x32x16_bf16 v[32:47], v[64:67], v[156:159], v[32:47]
	ds_read_b64_tr_b16 v[156:157], v203 offset:0x600
	ds_read_b64_tr_b16 v[158:159], v203 offset:0xe00
	v_mfma_f32_32x32x16_bf16 v[32:47], v[68:71], v[160:163], v[32:47]
	ds_read_b64_tr_b16 v[160:161], v203 offset:0x1600
	ds_read_b64_tr_b16 v[162:163], v203 offset:0x1e00
	v_mfma_f32_32x32x16_bf16 v[32:47], v[72:75], v[164:167], v[32:47]
	ds_read_b64_tr_b16 v[164:165], v203 offset:0x2600
	ds_read_b64_tr_b16 v[166:167], v203 offset:0x2e00
	ds_read_b64_tr_b16 v[172:173], v203 offset:0x3600
	ds_read_b64_tr_b16 v[174:175], v203 offset:0x3e00
	s_waitcnt lgkmcnt(0)
	v_mfma_f32_32x32x16_bf16 v[32:47], v[76:79], v[168:171], v[32:47]
	v_mfma_f32_32x32x16_bf16 v[48:63], v[64:67], v[156:159], v[48:63]
	s_waitcnt vmcnt(0)
	v_exp_f32_e32 v80, v80
	v_exp_f32_e32 v81, v81
	v_exp_f32_e32 v82, v82
	v_exp_f32_e32 v83, v83
	v_exp_f32_e32 v84, v84
	v_exp_f32_e32 v85, v85
	v_mfma_f32_32x32x16_bf16 v[48:63], v[68:71], v[160:163], v[48:63]
	v_exp_f32_e32 v86, v86
	v_exp_f32_e32 v87, v87
	v_exp_f32_e32 v88, v88
	v_exp_f32_e32 v89, v89
	v_exp_f32_e32 v90, v90
	v_exp_f32_e32 v91, v91
	v_exp_f32_e32 v92, v92
	v_mfma_f32_32x32x16_bf16 v[48:63], v[72:75], v[164:167], v[48:63]
	v_exp_f32_e32 v93, v93
	v_exp_f32_e32 v94, v94
	v_exp_f32_e32 v95, v95
	s_waitcnt lgkmcnt(0)
	s_barrier
	v_mfma_f32_32x32x16_bf16 v[48:63], v[76:79], v[172:175], v[48:63]
	v_mfma_f32_32x32x16_bf16 v[64:79], v[124:127], v[108:111], 0
	v_mfma_f32_32x32x16_bf16 v[64:79], v[120:123], v[104:107], v[64:79]
	v_add_f32_e32 v104, 0, v186
	v_add_f32_e32 v105, 0, v187
	v_add_f32_e32 v104, v188, v104
	v_add_f32_e32 v105, v189, v105
	v_add_f32_e32 v104, v190, v104
	v_add_f32_e32 v105, v191, v105
	v_add_f32_e32 v104, v192, v104
	v_mfma_f32_32x32x16_bf16 v[64:79], v[116:119], v[100:103], v[64:79]
	v_add_f32_e32 v100, v193, v105
	v_add_f32_e32 v100, v100, v104
	v_add_f32_e32 v100, v194, v100
	v_add_f32_e32 v100, v134, v100
	v_mfma_f32_32x32x16_bf16 v[64:79], v[112:115], v[96:99], v[64:79]
	s_nop 11
	v_exp_f32_e32 v96, v64
	v_exp_f32_e32 v65, v65
	v_exp_f32_e32 v99, v68
	v_exp_f32_e32 v97, v66
	v_exp_f32_e32 v101, v69
	v_exp_f32_e32 v98, v67
	v_exp_f32_e32 v102, v70
	v_exp_f32_e32 v103, v71
	v_add_f32_e32 v64, v80, v96
	v_exp_f32_e32 v104, v72
	v_add_f32_e32 v64, 0, v64
	v_add_f32_e32 v66, v81, v65
	v_add_f32_e32 v69, v84, v99
	v_exp_f32_e32 v105, v73
	v_add_f32_e32 v66, 0, v66
	v_add_f32_e32 v67, v82, v97
	v_add_f32_e32 v64, v69, v64
	v_add_f32_e32 v69, v85, v101
	v_exp_f32_e32 v106, v74
	v_add_f32_e32 v67, 0, v67
	v_add_f32_e32 v68, v83, v98
	v_add_f32_e32 v66, v69, v66
	v_add_f32_e32 v69, v86, v102
	v_exp_f32_e32 v107, v75
	v_add_f32_e32 v68, 0, v68
	v_add_f32_e32 v67, v69, v67
	v_add_f32_e32 v69, v87, v103
	v_exp_f32_e32 v108, v76
	v_add_f32_e32 v68, v69, v68
	v_add_f32_e32 v69, v88, v104
	v_exp_f32_e32 v109, v77
	v_add_f32_e32 v64, v69, v64
	v_add_f32_e32 v69, v89, v105
	v_exp_f32_e32 v110, v78
	v_add_f32_e32 v66, v69, v66
	v_add_f32_e32 v69, v90, v106
	v_exp_f32_e32 v111, v79
	v_add_f32_e32 v67, v69, v67
	v_add_f32_e32 v69, v91, v107
	v_add_f32_e32 v68, v69, v68
	v_add_f32_e32 v69, v92, v108
	v_add_f32_e32 v64, v69, v64
	v_add_f32_e32 v69, v93, v109
	v_add_f32_e32 v66, v69, v66
	v_add_f32_e32 v69, v94, v110
	v_add_f32_e32 v67, v69, v67
	v_add_f32_e32 v69, v95, v111
	v_add_f32_e32 v68, v69, v68
	v_add_f32_e32 v64, v66, v64
	v_add_f32_e32 v66, v68, v67
	v_add_f32_e32 v64, v66, v64
	v_cvt_pk_bf16_f32 v66, v80, v81
	v_cvt_pk_bf16_f32 v67, v82, v83
	v_cvt_pk_bf16_f32 v68, v84, v85
	v_cvt_pk_bf16_f32 v69, v86, v87
	v_add_f32_e32 v64, v100, v64
	v_permlane32_swap_b32_e32 v66, v68
	v_permlane32_swap_b32_e32 v67, v69
	v_cvt_pk_bf16_f32 v70, v88, v89
	v_cvt_pk_bf16_f32 v71, v90, v91
	v_cvt_pk_bf16_f32 v72, v92, v93
	v_cvt_pk_bf16_f32 v73, v94, v95
	v_cvt_pk_bf16_f32 v74, v96, v65
	v_cvt_pk_bf16_f32 v75, v97, v98
	v_cvt_pk_bf16_f32 v76, v99, v101
	v_cvt_pk_bf16_f32 v77, v102, v103
	v_cvt_pk_bf16_f32 v78, v104, v105
	v_cvt_pk_bf16_f32 v79, v106, v107
	v_cvt_pk_bf16_f32 v80, v108, v109
	v_cvt_pk_bf16_f32 v81, v110, v111
	s_nop 0
	v_permlane32_swap_b32_e32 v70, v72
	v_permlane32_swap_b32_e32 v71, v73
	v_permlane32_swap_b32_e32 v74, v76
	v_permlane32_swap_b32_e32 v75, v77
	v_permlane32_swap_b32_e32 v78, v80
	v_permlane32_swap_b32_e32 v79, v81
	ds_read_b64_tr_b16 v[82:83], v204 offset:0
	ds_read_b64_tr_b16 v[84:85], v204 offset:0x800
	ds_read_b64_tr_b16 v[86:87], v204 offset:0x1000
	ds_read_b64_tr_b16 v[88:89], v204 offset:0x1800
	ds_read_b64_tr_b16 v[90:91], v204 offset:0x2000
	ds_read_b64_tr_b16 v[92:93], v204 offset:0x2800
	ds_read_b64_tr_b16 v[94:95], v204 offset:0x3000
	ds_read_b64_tr_b16 v[96:97], v204 offset:0x3800
	s_waitcnt lgkmcnt(0)
; __device__ __forceinline__ unsigned cvt_pk_bf16(float lo, float hi) { unsigned r; asm volatile("v_cvt_pk_bf16_f32 %0, %1, %2" : "=v"(r) : "v"(lo), "v"(hi)); return r; }
; __device__ __forceinline__ int crow(int r, int hi) { return (r & 3) + 8 * (r >> 2) + 4 * hi; }
;     ...
;     pv_d0(o, vb0 + SHM_V, pa0, pa1, pa2, pa3);
;     __builtin_amdgcn_s_setprio(0);
;     (void)dummy_m;
;     { auto rr = __builtin_amdgcn_permlane32_swap(__float_as_uint(l_reg), __float_as_uint(l_reg), false, false); l_reg = __uint_as_float(rr[0]) + __uint_as_float(rr[1]); }
;     {
;         int t2 = threadIdx.x; asm volatile("" : "+v"(t2));
;         const int wid2 = t2 >> 6, lane2 = t2 & 63, r32b = lane2 & 31, hib = lane2 >> 5;
;         float* li2 = (float*)(lds + OFF_WS) + wid2 * 64;
;         if (hib == 0) li2[r32b] = l_reg; asm volatile("s_waitcnt lgkmcnt(0)" ::: "memory");
;         __syncthreads();
;         bf16_t* stash = (bf16_t*)(lds + OFF_Q) + wid2 * 4096;
;         bf16_t* stg = (mode == 1) ? stash : ((bf16_t*)lds + wid2 * 4096);
; #pragma unroll
;         for (int r = 0; r < 16; ++r) { const int orow = crow(r, hib); const float rl = __builtin_amdgcn_rcpf(li2[orow]);
; #pragma unroll
;             for (int d0 = 0; d0 < 4; ++d0) { const float v = o[d0][r] * rl; stg[orow * 128 + d0 * 32 + r32b] = (bf16_t)(cvt_pk_bf16(v, v) & 0xffffu); } }
;         asm volatile("s_waitcnt lgkmcnt(0)" ::: "memory");
	s_nop 0
	v_mfma_f32_32x32x16_bf16 v[0:15], v[66:69], v[82:85], v[0:15]
	ds_read_b64_tr_b16 v[82:83], v204 offset:0x200
	ds_read_b64_tr_b16 v[84:85], v204 offset:0xa00
	v_mfma_f32_32x32x16_bf16 v[0:15], v[70:73], v[86:89], v[0:15]
	ds_read_b64_tr_b16 v[86:87], v204 offset:0x1200
	ds_read_b64_tr_b16 v[88:89], v204 offset:0x1a00
	v_mfma_f32_32x32x16_bf16 v[0:15], v[74:77], v[90:93], v[0:15]
	ds_read_b64_tr_b16 v[90:91], v204 offset:0x2200
	ds_read_b64_tr_b16 v[92:93], v204 offset:0x2a00
	ds_read_b64_tr_b16 v[98:99], v204 offset:0x3200
	ds_read_b64_tr_b16 v[100:101], v204 offset:0x3a00
	s_waitcnt lgkmcnt(0)
	v_mfma_f32_32x32x16_bf16 v[0:15], v[78:81], v[94:97], v[0:15]
	v_mfma_f32_32x32x16_bf16 v[16:31], v[66:69], v[82:85], v[16:31]
	ds_read_b64_tr_b16 v[82:83], v204 offset:0x400
	ds_read_b64_tr_b16 v[84:85], v204 offset:0xc00
	v_mfma_f32_32x32x16_bf16 v[16:31], v[70:73], v[86:89], v[16:31]
	ds_read_b64_tr_b16 v[86:87], v204 offset:0x1400
	ds_read_b64_tr_b16 v[88:89], v204 offset:0x1c00
	v_mfma_f32_32x32x16_bf16 v[16:31], v[74:77], v[90:93], v[16:31]
	ds_read_b64_tr_b16 v[90:91], v204 offset:0x2400
	ds_read_b64_tr_b16 v[92:93], v204 offset:0x2c00
	ds_read_b64_tr_b16 v[94:95], v204 offset:0x3400
	ds_read_b64_tr_b16 v[96:97], v204 offset:0x3c00
	s_waitcnt lgkmcnt(0)
	v_mfma_f32_32x32x16_bf16 v[16:31], v[78:81], v[98:101], v[16:31]
	v_mfma_f32_32x32x16_bf16 v[32:47], v[66:69], v[82:85], v[32:47]
	ds_read_b64_tr_b16 v[82:83], v204 offset:0x600
	ds_read_b64_tr_b16 v[84:85], v204 offset:0xe00
	v_mfma_f32_32x32x16_bf16 v[32:47], v[70:73], v[86:89], v[32:47]
	ds_read_b64_tr_b16 v[86:87], v204 offset:0x1600
	ds_read_b64_tr_b16 v[88:89], v204 offset:0x1e00
	v_mfma_f32_32x32x16_bf16 v[32:47], v[74:77], v[90:93], v[32:47]
	ds_read_b64_tr_b16 v[90:91], v204 offset:0x2600
	ds_read_b64_tr_b16 v[92:93], v204 offset:0x2e00
	ds_read_b64_tr_b16 v[98:99], v204 offset:0x3600
	ds_read_b64_tr_b16 v[100:101], v204 offset:0x3e00
	s_waitcnt lgkmcnt(0)
	v_mfma_f32_32x32x16_bf16 v[32:47], v[78:81], v[94:97], v[32:47]
	v_mfma_f32_32x32x16_bf16 v[48:63], v[66:69], v[82:85], v[48:63]
	v_mfma_f32_32x32x16_bf16 v[48:63], v[70:73], v[86:89], v[48:63]
	v_mfma_f32_32x32x16_bf16 v[48:63], v[74:77], v[90:93], v[48:63]
	v_mfma_f32_32x32x16_bf16 v[48:63], v[78:81], v[98:101], v[48:63]
	s_setprio 0
	v_mov_b32_e32 v66, v218
	v_mov_b32_e32 v68, v64
	s_nop 1
	v_permlane32_swap_b32_e32 v64, v68
	v_and_b32_e32 v69, 32, v66
	v_and_b32_e32 v67, 0x3fffffc0, v66
	v_and_b32_e32 v65, 31, v66
	v_lshl_add_u32 v67, v67, 2, s35
	v_cmp_eq_u32_e32 vcc, 0, v69
	s_and_saveexec_b64 s[0:1], vcc
	v_add_f32_e32 v64, v64, v68
	v_lshl_add_u32 v68, v65, 2, v67
	ds_write_b32 v68, v64
	s_or_b64 exec, exec, s[0:1]
	v_lshrrev_b32_e32 v64, 3, v66
	v_and_b32_e32 v64, 4, v64
	v_lshl_add_u32 v67, v64, 2, v67
	s_waitcnt lgkmcnt(0)
	s_waitcnt lgkmcnt(0)
	s_barrier
	ds_read_b32 v68, v67
	v_lshlrev_b32_e32 v66, 7, v66
	v_and_b32_e32 v66, 0xffffe000, v66
	s_add_i32 s48, 0, 0x10800
	v_add_u32_e32 v66, s48, v66
	s_waitcnt lgkmcnt(0)
	v_rcp_f32_e32 v68, v68
	v_lshlrev_b32_e32 v65, 1, v65
	v_lshlrev_b32_e32 v64, 8, v64
	v_add3_u32 v64, v66, v65, v64
	v_mul_f32_e32 v0, v0, v68
	v_cvt_pk_bf16_f32 v0, v0, v0
	ds_write_b16 v64, v0
	v_mul_f32_e32 v0, v16, v68
	v_cvt_pk_bf16_f32 v0, v0, v0
	ds_write_b16 v64, v0 offset:64
	v_mul_f32_e32 v0, v32, v68
	v_cvt_pk_bf16_f32 v0, v0, v0
	ds_write_b16 v64, v0 offset:128
	v_mul_f32_e32 v0, v48, v68
	v_cvt_pk_bf16_f32 v0, v0, v0
	ds_read_b32 v16, v67 offset:4
	ds_write_b16 v64, v0 offset:192
	v_readfirstlane_b32 s49, v202
	s_lshl_b32 s55, s49, 10
	s_cmp_lg_u32 0, -1
	s_waitcnt lgkmcnt(1)
	v_rcp_f32_e32 v16, v16
	s_cselect_b32 s0, 0, 0
	s_add_i32 s0, s0, s55
	s_add_i32 s0, s0, 0x8000
	v_mul_f32_e32 v0, v1, v16
	v_cvt_pk_bf16_f32 v0, v0, v0
	ds_write_b16 v64, v0 offset:256
	v_mul_f32_e32 v0, v17, v16
	v_cvt_pk_bf16_f32 v0, v0, v0
	ds_write_b16 v64, v0 offset:320
	v_mul_f32_e32 v0, v33, v16
	v_cvt_pk_bf16_f32 v0, v0, v0
	ds_write_b16 v64, v0 offset:384
	v_mul_f32_e32 v0, v49, v16
	v_cvt_pk_bf16_f32 v0, v0, v0
	ds_read_b32 v1, v67 offset:8
	ds_write_b16 v64, v0 offset:448
	s_waitcnt lgkmcnt(1)
	v_rcp_f32_e32 v1, v1
	s_nop 0
	v_mul_f32_e32 v0, v2, v1
	v_cvt_pk_bf16_f32 v0, v0, v0
	ds_write_b16 v64, v0 offset:512
	v_mul_f32_e32 v0, v18, v1
	v_cvt_pk_bf16_f32 v0, v0, v0
	ds_write_b16 v64, v0 offset:576
	v_mul_f32_e32 v0, v34, v1
	v_cvt_pk_bf16_f32 v0, v0, v0
	ds_write_b16 v64, v0 offset:640
	v_mul_f32_e32 v0, v50, v1
	v_cvt_pk_bf16_f32 v0, v0, v0
	ds_read_b32 v1, v67 offset:12
	ds_write_b16 v64, v0 offset:704
	s_waitcnt lgkmcnt(1)
	v_rcp_f32_e32 v1, v1
	s_nop 0
	v_mul_f32_e32 v0, v3, v1
	v_cvt_pk_bf16_f32 v0, v0, v0
	ds_write_b16 v64, v0 offset:768
	v_mul_f32_e32 v0, v19, v1
	v_cvt_pk_bf16_f32 v0, v0, v0
	ds_write_b16 v64, v0 offset:832
	v_mul_f32_e32 v0, v35, v1
	v_cvt_pk_bf16_f32 v0, v0, v0
	ds_write_b16 v64, v0 offset:896
	v_mul_f32_e32 v0, v51, v1
	v_cvt_pk_bf16_f32 v0, v0, v0
	ds_read_b32 v1, v67 offset:32
	ds_write_b16 v64, v0 offset:960
	s_waitcnt lgkmcnt(1)
	v_rcp_f32_e32 v1, v1
	s_nop 0
	v_mul_f32_e32 v0, v4, v1
	v_cvt_pk_bf16_f32 v0, v0, v0
	ds_write_b16 v64, v0 offset:2048
	v_mul_f32_e32 v0, v20, v1
	v_cvt_pk_bf16_f32 v0, v0, v0
	ds_write_b16 v64, v0 offset:2112
	v_mul_f32_e32 v0, v36, v1
	v_cvt_pk_bf16_f32 v0, v0, v0
	ds_write_b16 v64, v0 offset:2176
	v_mul_f32_e32 v0, v52, v1
	v_cvt_pk_bf16_f32 v0, v0, v0
	ds_read_b32 v1, v67 offset:36
	ds_write_b16 v64, v0 offset:2240
	s_waitcnt lgkmcnt(1)
; __device__ __forceinline__ int crow(int r, int hi) { return (r & 3) + 8 * (r >> 2) + 4 * hi; }
;     ...
;     {
;         const bf16_t* Qw = Qb + (size_t)(wid * QBLK + r32) * LDQ + hi * 8;
; #pragma unroll
;         for (int d0 = 0; d0 < NREG; ++d0) qr[d0] = *(const bf16x8*)(Qw + d0 * 16);
; #pragma unroll
;         for (int d0 = NREG; d0 < ND0; ++d0) *(bf16x8*)(qs + (d0 - NREG) * 1024) = *(const bf16x8*)(Qw + d0 * 16);
;     }
;     const int widu = __builtin_amdgcn_readfirstlane(wid);
;     const int vb0 = (int)(uintptr_t)V_lds + v_rd_base(lane);
;     unsigned ksrc[2], vsrc[2];
; #pragma unroll
;     for (int i = 0; i < 2; ++i) {
;     ...
;         bf16_t* stash = (bf16_t*)(lds + OFF_Q) + wid2 * 4096;
;         bf16_t* stg = (mode == 1) ? stash : ((bf16_t*)lds + wid2 * 4096);
; #pragma unroll
;         for (int r = 0; r < 16; ++r) { const int orow = crow(r, hib); const float rl = __builtin_amdgcn_rcpf(li2[orow]);
; #pragma unroll
;             for (int d0 = 0; d0 < 4; ++d0) { const float v = o[d0][r] * rl; stg[orow * 128 + d0 * 32 + r32b] = (bf16_t)(cvt_pk_bf16(v, v) & 0xffffu); } }
;         asm volatile("s_waitcnt lgkmcnt(0)" ::: "memory");
;         if (mode != 1) {
;             bf16_t* Ow = Ob + (size_t)(wid2 * QBLK) * LDO;
;             const int ch = lane2 & 15;
;             float gg[8];
;             if (mode == 2) {
; #pragma unroll
;                 for (int e = 0; e < 8; ++e) gg[e] = sg[ch * 8 + e] * 0.8f; }
; #pragma unroll
;             for (int i = 0; i < 8; ++i) { const int row = i * 4 + (lane2 >> 4); u32x4 v = *(const u32x4*)(stg + row * 128 + ch * 8);
;                 if (mode == 2) { const u32x4 v0 = *(const u32x4*)(stash + row * 128 + ch * 8); float x0[8], x1[8]; unpack8(v0, x0); unpack8(v, x1); float ss = 0.f;
; #pragma unroll
;                     for (int e = 0; e < 8; ++e) { x0[e] = x0[e] - lam * x1[e]; ss += x0[e] * x0[e]; }
;                     ss += __shfl_xor(ss, 1); ss += __shfl_xor(ss, 2); ss += __shfl_xor(ss, 4); ss += __shfl_xor(ss, 8);
;                     const float rstd = rsqrtf(ss * (1.0f / 128) + EPS);
; #pragma unroll
;                     for (int e = 0; e < 8; ++e) x0[e] = x0[e] * rstd * gg[e];
;                     v = pack8(x0); }
;                 *(u32x4*)(Ow + (size_t)row * LDO + ch * 8) = v; }
;         }
;     }
;     asm volatile("s_waitcnt vmcnt(0)" ::: "memory");
;     __syncthreads();
	v_rcp_f32_e32 v1, v1
	s_nop 0
	v_mul_f32_e32 v0, v5, v1
	v_cvt_pk_bf16_f32 v0, v0, v0
	ds_write_b16 v64, v0 offset:2304
	v_mul_f32_e32 v0, v21, v1
	v_cvt_pk_bf16_f32 v0, v0, v0
	ds_write_b16 v64, v0 offset:2368
	v_mul_f32_e32 v0, v37, v1
	v_cvt_pk_bf16_f32 v0, v0, v0
	ds_write_b16 v64, v0 offset:2432
	v_mul_f32_e32 v0, v53, v1
	v_cvt_pk_bf16_f32 v0, v0, v0
	ds_read_b32 v1, v67 offset:40
	ds_write_b16 v64, v0 offset:2496
	s_waitcnt lgkmcnt(1)
	v_rcp_f32_e32 v1, v1
	s_nop 0
	v_mul_f32_e32 v0, v6, v1
	v_cvt_pk_bf16_f32 v0, v0, v0
	ds_write_b16 v64, v0 offset:2560
	v_mul_f32_e32 v0, v22, v1
	v_cvt_pk_bf16_f32 v0, v0, v0
	ds_write_b16 v64, v0 offset:2624
	v_mul_f32_e32 v0, v38, v1
	v_cvt_pk_bf16_f32 v0, v0, v0
	ds_write_b16 v64, v0 offset:2688
	v_mul_f32_e32 v0, v54, v1
	v_cvt_pk_bf16_f32 v0, v0, v0
	ds_read_b32 v1, v67 offset:44
	ds_write_b16 v64, v0 offset:2752
	s_waitcnt lgkmcnt(1)
	v_rcp_f32_e32 v1, v1
	s_nop 0
	v_mul_f32_e32 v0, v7, v1
	v_cvt_pk_bf16_f32 v0, v0, v0
	ds_write_b16 v64, v0 offset:2816
	v_mul_f32_e32 v0, v23, v1
	v_cvt_pk_bf16_f32 v0, v0, v0
	ds_write_b16 v64, v0 offset:2880
	v_mul_f32_e32 v0, v39, v1
	v_cvt_pk_bf16_f32 v0, v0, v0
	ds_write_b16 v64, v0 offset:2944
	v_mul_f32_e32 v0, v55, v1
	v_cvt_pk_bf16_f32 v0, v0, v0
	ds_read_b32 v1, v67 offset:64
	ds_write_b16 v64, v0 offset:3008
	s_waitcnt lgkmcnt(1)
	v_rcp_f32_e32 v1, v1
	s_nop 0
	v_mul_f32_e32 v0, v8, v1
	v_cvt_pk_bf16_f32 v0, v0, v0
	ds_write_b16 v64, v0 offset:4096
	v_mul_f32_e32 v0, v24, v1
	v_cvt_pk_bf16_f32 v0, v0, v0
	ds_write_b16 v64, v0 offset:4160
	v_mul_f32_e32 v0, v40, v1
	v_cvt_pk_bf16_f32 v0, v0, v0
	ds_write_b16 v64, v0 offset:4224
	v_mul_f32_e32 v0, v56, v1
	v_cvt_pk_bf16_f32 v0, v0, v0
	ds_read_b32 v1, v67 offset:68
	ds_write_b16 v64, v0 offset:4288
	s_waitcnt lgkmcnt(1)
	v_rcp_f32_e32 v1, v1
	s_nop 0
	v_mul_f32_e32 v0, v9, v1
	v_cvt_pk_bf16_f32 v0, v0, v0
	ds_write_b16 v64, v0 offset:4352
	v_mul_f32_e32 v0, v25, v1
	v_cvt_pk_bf16_f32 v0, v0, v0
	ds_write_b16 v64, v0 offset:4416
	v_mul_f32_e32 v0, v41, v1
	v_cvt_pk_bf16_f32 v0, v0, v0
	ds_write_b16 v64, v0 offset:4480
	v_mul_f32_e32 v0, v57, v1
	v_cvt_pk_bf16_f32 v0, v0, v0
	ds_read_b32 v1, v67 offset:72
	ds_write_b16 v64, v0 offset:4544
	s_waitcnt lgkmcnt(1)
	v_rcp_f32_e32 v1, v1
	s_nop 0
	v_mul_f32_e32 v0, v10, v1
	v_cvt_pk_bf16_f32 v0, v0, v0
	ds_write_b16 v64, v0 offset:4608
	v_mul_f32_e32 v0, v26, v1
	v_cvt_pk_bf16_f32 v0, v0, v0
	ds_write_b16 v64, v0 offset:4672
	v_mul_f32_e32 v0, v42, v1
	v_cvt_pk_bf16_f32 v0, v0, v0
	ds_write_b16 v64, v0 offset:4736
	v_mul_f32_e32 v0, v58, v1
	v_cvt_pk_bf16_f32 v0, v0, v0
	ds_read_b32 v1, v67 offset:76
	ds_write_b16 v64, v0 offset:4800
	s_waitcnt lgkmcnt(1)
	v_rcp_f32_e32 v1, v1
	s_nop 0
	v_mul_f32_e32 v0, v11, v1
	v_cvt_pk_bf16_f32 v0, v0, v0
	ds_write_b16 v64, v0 offset:4864
	v_mul_f32_e32 v0, v27, v1
	v_cvt_pk_bf16_f32 v0, v0, v0
	ds_write_b16 v64, v0 offset:4928
	v_mul_f32_e32 v0, v43, v1
	v_cvt_pk_bf16_f32 v0, v0, v0
	ds_write_b16 v64, v0 offset:4992
	v_mul_f32_e32 v0, v59, v1
	v_cvt_pk_bf16_f32 v0, v0, v0
	ds_read_b32 v1, v67 offset:96
	ds_write_b16 v64, v0 offset:5056
	s_waitcnt lgkmcnt(1)
	v_rcp_f32_e32 v1, v1
	s_nop 0
	v_mul_f32_e32 v0, v12, v1
	v_cvt_pk_bf16_f32 v0, v0, v0
	ds_write_b16 v64, v0 offset:6144
	v_mul_f32_e32 v0, v28, v1
	v_cvt_pk_bf16_f32 v0, v0, v0
	ds_write_b16 v64, v0 offset:6208
	v_mul_f32_e32 v0, v44, v1
	v_cvt_pk_bf16_f32 v0, v0, v0
	ds_write_b16 v64, v0 offset:6272
	v_mul_f32_e32 v0, v60, v1
	v_cvt_pk_bf16_f32 v0, v0, v0
	ds_read_b32 v1, v67 offset:100
	ds_write_b16 v64, v0 offset:6336
	s_waitcnt lgkmcnt(1)
	v_rcp_f32_e32 v1, v1
	s_nop 0
	v_mul_f32_e32 v0, v13, v1
	v_cvt_pk_bf16_f32 v0, v0, v0
	ds_write_b16 v64, v0 offset:6400
	v_mul_f32_e32 v0, v29, v1
	v_cvt_pk_bf16_f32 v0, v0, v0
	ds_write_b16 v64, v0 offset:6464
	v_mul_f32_e32 v0, v45, v1
	v_cvt_pk_bf16_f32 v0, v0, v0
	ds_write_b16 v64, v0 offset:6528
	v_mul_f32_e32 v0, v61, v1
	v_cvt_pk_bf16_f32 v0, v0, v0
	ds_read_b32 v1, v67 offset:104
	ds_write_b16 v64, v0 offset:6592
	s_waitcnt lgkmcnt(1)
	v_rcp_f32_e32 v1, v1
	s_nop 0
	v_mul_f32_e32 v0, v14, v1
	v_cvt_pk_bf16_f32 v0, v0, v0
	ds_write_b16 v64, v0 offset:6656
	v_mul_f32_e32 v0, v30, v1
	v_cvt_pk_bf16_f32 v0, v0, v0
	ds_write_b16 v64, v0 offset:6720
	v_mul_f32_e32 v0, v46, v1
	v_cvt_pk_bf16_f32 v0, v0, v0
	ds_write_b16 v64, v0 offset:6784
	v_mul_f32_e32 v0, v62, v1
	v_cvt_pk_bf16_f32 v0, v0, v0
	ds_read_b32 v1, v67 offset:108
	ds_write_b16 v64, v0 offset:6848
	s_waitcnt lgkmcnt(1)
	v_rcp_f32_e32 v1, v1
	s_nop 0
	v_mul_f32_e32 v0, v15, v1
	v_cvt_pk_bf16_f32 v0, v0, v0
	ds_write_b16 v64, v0 offset:6912
	v_mul_f32_e32 v0, v31, v1
	v_cvt_pk_bf16_f32 v0, v0, v0
	ds_write_b16 v64, v0 offset:6976
	v_mul_f32_e32 v0, v47, v1
	v_cvt_pk_bf16_f32 v0, v0, v0
	ds_write_b16 v64, v0 offset:7040
	v_mul_f32_e32 v0, v63, v1
	v_cvt_pk_bf16_f32 v0, v0, v0
	ds_write_b16 v64, v0 offset:7104
	s_waitcnt lgkmcnt(0)
	s_waitcnt vmcnt(0)
	s_waitcnt lgkmcnt(0)
	s_barrier
	global_load_dwordx4 v[108:111], v[144:145], off offset:128
	global_load_dwordx4 v[104:107], v[144:145], off offset:160
	global_load_dwordx4 v[100:103], v[144:145], off offset:192
	global_load_dwordx4 v[96:99], v[144:145], off offset:224
	v_lshl_add_u64 v[0:1], v[150:151], 0, s[42:43]
	s_mov_b32 s1, m0
	s_mov_b32 m0, s0
	s_nop 0
	global_load_lds_dwordx4 v[0:1], off
	s_mov_b32 m0, s1
	s_waitcnt vmcnt(0)
	s_nop 0
	v_readfirstlane_b32 s1, v218
	s_cmpk_lt_i32 s1, 0x100
	s_barrier
	s_cbranch_scc1 .LBB0_566
	s_setprio 1

; #define SBAR() __builtin_amdgcn_sched_barrier(0)
; template <bool FAST> __device__ __forceinline__ void finishSM(f32x16& p0, f32x16& p1, float alpha, float& l_reg, bf16x8& pa0, bf16x8& pa1, bf16x8& pa2, bf16x8& pa3) {
;     ...
;     if (FAST) { float s0 = 0.f, s1 = 0.f, s2 = 0.f, s3 = 0.f;
; #pragma unroll
;         for (int r = 0; r < 16; r += 4) { s0 += p0[r] + p1[r]; s1 += p0[r + 1] + p1[r + 1]; s2 += p0[r + 2] + p1[r + 2]; s3 += p0[r + 3] + p1[r + 3]; }
;         ps = (s0 + s1) + (s2 + s3); }
;     else {
; #pragma unroll
;     for (int r = 0; r < 16; ++r) ps += p0[r];
; #pragma unroll
;     for (int r = 0; r < 16; ++r) ps += p1[r];
;     }
;     if (FAST) { SBAR(); l_reg += ps; }
;     else { auto rr = __builtin_amdgcn_permlane32_swap(__float_as_uint(ps), __float_as_uint(ps), false, false);
;            ps = __uint_as_float(rr[0]) + __uint_as_float(rr[1]); l_reg = l_reg * alpha + ps; }
;     ...
;     PK4(p0, 0, pa0); PK4(p0, 8, pa1); PK4(p1, 0, pa2); PK4(p1, 8, pa3);
; template <int D0> __device__ __forceinline__ void pv_one(f32x16& od, int vb, bf16x8 pa0, bf16x8 pa1, bf16x8 pa2, bf16x8 pa3) {
;     const s16x4 l0 = tr_read<v_rd_off(D0, 0, 0)>(vb), h0 = tr_read<v_rd_off(D0, 0, 1)>(vb), l1 = tr_read<v_rd_off(D0, 1, 0)>(vb), h1 = tr_read<v_rd_off(D0, 1, 1)>(vb);
;     const s16x4 l2 = tr_read<v_rd_off(D0, 2, 0)>(vb), h2 = tr_read<v_rd_off(D0, 2, 1)>(vb), l3 = tr_read<v_rd_off(D0, 3, 0)>(vb), h3 = tr_read<v_rd_off(D0, 3, 1)>(vb);
;     asm volatile("s_waitcnt lgkmcnt(0)" ::: "memory"); SBAR();
;     ...
;     od = __builtin_amdgcn_mfma_f32_32x32x16_bf16(pa0, PK(l0, h0), od, 0, 0, 0);
;     od = __builtin_amdgcn_mfma_f32_32x32x16_bf16(pa1, PK(l1, h1), od, 0, 0, 0);
;     od = __builtin_amdgcn_mfma_f32_32x32x16_bf16(pa2, PK(l2, h2), od, 0, 0, 0);
;     od = __builtin_amdgcn_mfma_f32_32x32x16_bf16(pa3, PK(l3, h3), od, 0, 0, 0);
;     ...
; }
; __device__ __forceinline__ void pv_d0(f32x16* o, int vb, bf16x8 pa0, bf16x8 pa1, bf16x8 pa2, bf16x8 pa3) {
;     pv_one<0>(o[0], vb, pa0, pa1, pa2, pa3); pv_one<1>(o[1], vb, pa0, pa1, pa2, pa3); pv_one<2>(o[2], vb, pa0, pa1, pa2, pa3); pv_one<3>(o[3], vb, pa0, pa1, pa2, pa3);
.LBB0_567:
	v_lshl_add_u64 v[80:81], v[142:143], 0, s[22:23]
	s_mov_b32 s74, m0
	s_mov_b32 m0, s0
	s_nop 0
	global_load_lds_dwordx4 v[80:81], off
	s_mov_b32 m0, s74
	s_cmp_lg_u32 0, -1
	s_cselect_b32 s74, 0, 0
	s_add_i32 s74, s74, s49
	v_lshl_add_u64 v[180:181], s[46:47], 0, v[132:133]
	s_add_i32 s75, s74, 0x4000
	s_mov_b32 s76, m0
	s_mov_b32 m0, s75
	s_nop 0
	global_load_lds_dwordx4 v[180:181], off
	s_mov_b32 m0, s76
	v_lshl_add_u64 v[80:81], v[180:181], 0, s[20:21]
	s_addk_i32 s74, 0x4400
	s_mov_b32 s75, m0
	s_mov_b32 m0, s74
	s_nop 0
	global_load_lds_dwordx4 v[80:81], off
	s_mov_b32 m0, s75
	ds_read_b128 v[80:83], v205 offset:40960
	ds_read_b128 v[124:127], v205 offset:45056
	ds_read_b128 v[112:115], v206 offset:40960
	ds_read_b128 v[120:123], v206 offset:45056
	s_waitcnt lgkmcnt(3)
	v_mfma_f32_32x32x16_bf16 v[80:95], v[80:83], v[108:111], 0
	s_waitcnt lgkmcnt(1)
	v_mfma_f32_32x32x16_bf16 v[80:95], v[112:115], v[104:107], v[80:95]
	ds_read_b128 v[112:115], v207 offset:40960
	ds_read_b128 v[116:119], v207 offset:45056
	s_waitcnt lgkmcnt(1)
	v_mfma_f32_32x32x16_bf16 v[80:95], v[112:115], v[100:103], v[80:95]
	ds_read_b128 v[164:167], v208 offset:40960
	ds_read_b128 v[112:115], v208 offset:45056
	s_waitcnt lgkmcnt(1)
	v_mfma_f32_32x32x16_bf16 v[80:95], v[164:167], v[96:99], v[80:95]
	v_exp_f32_e32 v193, v64
	v_exp_f32_e32 v191, v65
	v_exp_f32_e32 v192, v66
	v_exp_f32_e32 v190, v67
	v_exp_f32_e32 v67, v69
	v_exp_f32_e32 v66, v71
	v_exp_f32_e32 v65, v72
	v_exp_f32_e32 v64, v74
	v_exp_f32_e32 v189, v68
	v_exp_f32_e32 v188, v70
	v_exp_f32_e32 v187, v73
	v_exp_f32_e32 v186, v75
	v_exp_f32_e32 v185, v76
	v_exp_f32_e32 v183, v77
	v_exp_f32_e32 v184, v78
	v_exp_f32_e32 v182, v79
	v_cvt_pk_bf16_f32 v68, v163, v161
	v_cvt_pk_bf16_f32 v69, v162, v160
	v_cvt_pk_bf16_f32 v70, v159, v157
	v_cvt_pk_bf16_f32 v71, v158, v156
	v_cvt_pk_bf16_f32 v72, v151, v149
	v_cvt_pk_bf16_f32 v73, v150, v148
	v_cvt_pk_bf16_f32 v74, v147, v145
	v_cvt_pk_bf16_f32 v75, v146, v144
	v_cvt_pk_bf16_f32 v76, v193, v191
	v_cvt_pk_bf16_f32 v77, v192, v190
	v_cvt_pk_bf16_f32 v78, v189, v67
	v_cvt_pk_bf16_f32 v79, v188, v66
	s_nop 0
	v_permlane32_swap_b32_e32 v68, v70
	v_permlane32_swap_b32_e32 v69, v71
	v_permlane32_swap_b32_e32 v72, v74
	v_permlane32_swap_b32_e32 v73, v75
	v_permlane32_swap_b32_e32 v76, v78
	v_permlane32_swap_b32_e32 v77, v79
	v_cvt_pk_bf16_f32 v194, v65, v187
	v_cvt_pk_bf16_f32 v195, v64, v186
	v_cvt_pk_bf16_f32 v196, v185, v183
	v_cvt_pk_bf16_f32 v197, v184, v182
	s_nop 0
	v_permlane32_swap_b32_e32 v194, v196
	v_permlane32_swap_b32_e32 v195, v197
	ds_read_b64_tr_b16 v[164:165], v203 offset:0
	ds_read_b64_tr_b16 v[166:167], v203 offset:0x800
	ds_read_b64_tr_b16 v[168:169], v203 offset:0x1000
	ds_read_b64_tr_b16 v[170:171], v203 offset:0x1800
	ds_read_b64_tr_b16 v[172:173], v203 offset:0x2000
	ds_read_b64_tr_b16 v[174:175], v203 offset:0x2800
	ds_read_b64_tr_b16 v[176:177], v203 offset:0x3000
	ds_read_b64_tr_b16 v[178:179], v203 offset:0x3800
	s_waitcnt lgkmcnt(0)
	s_nop 0
	v_mfma_f32_32x32x16_bf16 v[0:15], v[68:71], v[164:167], v[0:15]
	ds_read_b64_tr_b16 v[164:165], v203 offset:0x200
	ds_read_b64_tr_b16 v[166:167], v203 offset:0xa00
	v_mfma_f32_32x32x16_bf16 v[0:15], v[72:75], v[168:171], v[0:15]
	ds_read_b64_tr_b16 v[168:169], v203 offset:0x1200
	ds_read_b64_tr_b16 v[170:171], v203 offset:0x1a00
	v_mfma_f32_32x32x16_bf16 v[0:15], v[76:79], v[172:175], v[0:15]
	ds_read_b64_tr_b16 v[172:173], v203 offset:0x2200
	ds_read_b64_tr_b16 v[174:175], v203 offset:0x2a00
	ds_read_b64_tr_b16 v[198:199], v203 offset:0x3200
	ds_read_b64_tr_b16 v[200:201], v203 offset:0x3a00
	s_waitcnt lgkmcnt(0)
	v_mfma_f32_32x32x16_bf16 v[0:15], v[194:197], v[176:179], v[0:15]
	v_mfma_f32_32x32x16_bf16 v[16:31], v[68:71], v[164:167], v[16:31]
	ds_read_b64_tr_b16 v[164:165], v203 offset:0x400
	ds_read_b64_tr_b16 v[166:167], v203 offset:0xc00
	v_mfma_f32_32x32x16_bf16 v[16:31], v[72:75], v[168:171], v[16:31]
	ds_read_b64_tr_b16 v[168:169], v203 offset:0x1400
	ds_read_b64_tr_b16 v[170:171], v203 offset:0x1c00
	v_mfma_f32_32x32x16_bf16 v[16:31], v[76:79], v[172:175], v[16:31]
	ds_read_b64_tr_b16 v[172:173], v203 offset:0x2400
	ds_read_b64_tr_b16 v[174:175], v203 offset:0x2c00
	ds_read_b64_tr_b16 v[176:177], v203 offset:0x3400
	ds_read_b64_tr_b16 v[178:179], v203 offset:0x3c00
	s_waitcnt lgkmcnt(0)
	v_mfma_f32_32x32x16_bf16 v[16:31], v[194:197], v[198:201], v[16:31]
	v_mfma_f32_32x32x16_bf16 v[32:47], v[68:71], v[164:167], v[32:47]
	ds_read_b64_tr_b16 v[164:165], v203 offset:0x600
	ds_read_b64_tr_b16 v[166:167], v203 offset:0xe00
	v_mfma_f32_32x32x16_bf16 v[32:47], v[72:75], v[168:171], v[32:47]
	ds_read_b64_tr_b16 v[168:169], v203 offset:0x1600
	ds_read_b64_tr_b16 v[170:171], v203 offset:0x1e00
	ds_read_b64_tr_b16 v[198:199], v203 offset:0x2600
	ds_read_b64_tr_b16 v[200:201], v203 offset:0x2e00
	ds_read_b64_tr_b16 v[210:211], v203 offset:0x3600
	ds_read_b64_tr_b16 v[212:213], v203 offset:0x3e00
	s_waitcnt lgkmcnt(0)
	v_mfma_f32_32x32x16_bf16 v[32:47], v[76:79], v[172:175], v[32:47]
	v_mfma_f32_32x32x16_bf16 v[32:47], v[194:197], v[176:179], v[32:47]
	v_mfma_f32_32x32x16_bf16 v[48:63], v[68:71], v[164:167], v[48:63]
	v_exp_f32_e32 v174, v86
	v_exp_f32_e32 v172, v87
	v_add_f32_e32 v86, v156, v66
	v_add_f32_e32 v87, v157, v67
	v_exp_f32_e32 v179, v80
	v_exp_f32_e32 v177, v81
	v_exp_f32_e32 v178, v82
	v_exp_f32_e32 v176, v83
	v_mfma_f32_32x32x16_bf16 v[48:63], v[72:75], v[168:171], v[48:63]
	v_exp_f32_e32 v171, v88
	v_exp_f32_e32 v169, v89
	v_add_f32_e32 v88, v150, v64
	v_add_f32_e32 v89, v151, v65
	v_add_f32_e32 v80, v162, v192
	v_add_f32_e32 v81, v163, v193
	v_add_f32_e32 v82, v160, v190
	v_add_f32_e32 v83, v161, v191
	v_exp_f32_e32 v175, v84
	v_exp_f32_e32 v173, v85
	v_mfma_f32_32x32x16_bf16 v[48:63], v[76:79], v[198:201], v[48:63]
	v_add_f32_e64 v84, v158, v188
	v_add_f32_e64 v85, v159, v189
	v_exp_f32_e32 v170, v90
	v_exp_f32_e32 v168, v91
	v_add_f32_e32 v90, v148, v186
	v_add_f32_e32 v91, v149, v187
	v_add_f32_e32 v80, v84, v80
	v_add_f32_e32 v81, v85, v81
	v_mfma_f32_32x32x16_bf16 v[64:79], v[124:127], v[108:111], 0
	v_add_f32_e64 v82, v86, v82
	v_add_f32_e64 v83, v87, v83
	v_exp_f32_e32 v167, v92
	v_exp_f32_e32 v165, v93
	v_exp_f32_e32 v166, v94
	v_exp_f32_e32 v164, v95
	v_add_f32_e32 v92, v146, v184
	v_add_f32_e32 v93, v147, v185
	v_add_f32_e32 v94, v144, v182
	v_add_f32_e32 v95, v145, v183
	v_mfma_f32_32x32x16_bf16 v[64:79], v[120:123], v[104:107], v[64:79]
	v_add_f32_e64 v80, v88, v80
	v_add_f32_e64 v81, v89, v81
	v_add_f32_e64 v82, v90, v82
	v_add_f32_e64 v83, v91, v83
	v_add_f32_e64 v80, v92, v80
	v_add_f32_e64 v81, v93, v81
	v_add_f32_e32 v82, v94, v82
	v_add_f32_e32 v83, v95, v83
	s_waitcnt vmcnt(0)
	s_waitcnt lgkmcnt(0)
	v_add_f32_e32 v80, v82, v80
	v_add_f32_e32 v81, v83, v81
	v_mfma_f32_32x32x16_bf16 v[64:79], v[116:119], v[100:103], v[64:79]
	s_barrier
; #define SBAR() __builtin_amdgcn_sched_barrier(0)
; template <bool FAST> __device__ __forceinline__ void finishSM(f32x16& p0, f32x16& p1, float alpha, float& l_reg, bf16x8& pa0, bf16x8& pa1, bf16x8& pa2, bf16x8& pa3) {
;     ...
;     if (FAST) { float s0 = 0.f, s1 = 0.f, s2 = 0.f, s3 = 0.f;
; #pragma unroll
;         for (int r = 0; r < 16; r += 4) { s0 += p0[r] + p1[r]; s1 += p0[r + 1] + p1[r + 1]; s2 += p0[r + 2] + p1[r + 2]; s3 += p0[r + 3] + p1[r + 3]; }
;         ps = (s0 + s1) + (s2 + s3); }
;     else {
; #pragma unroll
;     for (int r = 0; r < 16; ++r) ps += p0[r];
; #pragma unroll
;     for (int r = 0; r < 16; ++r) ps += p1[r];
;     }
;     if (FAST) { SBAR(); l_reg += ps; }
;     else { auto rr = __builtin_amdgcn_permlane32_swap(__float_as_uint(ps), __float_as_uint(ps), false, false);
;            ps = __uint_as_float(rr[0]) + __uint_as_float(rr[1]); l_reg = l_reg * alpha + ps; }
;     ...
;     PK4(p0, 0, pa0); PK4(p0, 8, pa1); PK4(p1, 0, pa2); PK4(p1, 8, pa3);
; template <int D0> __device__ __forceinline__ void pv_one(f32x16& od, int vb, bf16x8 pa0, bf16x8 pa1, bf16x8 pa2, bf16x8 pa3) {
;     const s16x4 l0 = tr_read<v_rd_off(D0, 0, 0)>(vb), h0 = tr_read<v_rd_off(D0, 0, 1)>(vb), l1 = tr_read<v_rd_off(D0, 1, 0)>(vb), h1 = tr_read<v_rd_off(D0, 1, 1)>(vb);
;     const s16x4 l2 = tr_read<v_rd_off(D0, 2, 0)>(vb), h2 = tr_read<v_rd_off(D0, 2, 1)>(vb), l3 = tr_read<v_rd_off(D0, 3, 0)>(vb), h3 = tr_read<v_rd_off(D0, 3, 1)>(vb);
;     asm volatile("s_waitcnt lgkmcnt(0)" ::: "memory"); SBAR();
;     ...
;     od = __builtin_amdgcn_mfma_f32_32x32x16_bf16(pa0, PK(l0, h0), od, 0, 0, 0);
;     od = __builtin_amdgcn_mfma_f32_32x32x16_bf16(pa1, PK(l1, h1), od, 0, 0, 0);
;     od = __builtin_amdgcn_mfma_f32_32x32x16_bf16(pa2, PK(l2, h2), od, 0, 0, 0);
;     od = __builtin_amdgcn_mfma_f32_32x32x16_bf16(pa3, PK(l3, h3), od, 0, 0, 0);
;     ...
; }
; __device__ __forceinline__ void pv_d0(f32x16* o, int vb, bf16x8 pa0, bf16x8 pa1, bf16x8 pa2, bf16x8 pa3) {
;     pv_one<0>(o[0], vb, pa0, pa1, pa2, pa3); pv_one<1>(o[1], vb, pa0, pa1, pa2, pa3); pv_one<2>(o[2], vb, pa0, pa1, pa2, pa3); pv_one<3>(o[3], vb, pa0, pa1, pa2, pa3);
	s_mov_b32 s74, m0
	s_mov_b32 m0, s55
	s_nop 0
	global_load_lds_dwordx4 v[142:143], off
	s_mov_b32 m0, s74
	v_add_f32_e32 v141, v80, v81
	v_lshl_add_u64 v[80:81], v[180:181], 0, s[6:7]
	s_mov_b32 s74, m0
	s_mov_b32 m0, s72
	s_nop 0
	global_load_lds_dwordx4 v[80:81], off
	s_mov_b32 m0, s74
	v_lshl_add_u64 v[80:81], v[180:181], 0, s[26:27]
	v_mfma_f32_32x32x16_bf16 v[48:63], v[194:197], v[210:213], v[48:63]
	s_mov_b32 s74, m0
	s_mov_b32 m0, s73
	s_nop 0
	global_load_lds_dwordx4 v[80:81], off
	s_mov_b32 m0, s74
	v_mfma_f32_32x32x16_bf16 v[64:79], v[112:115], v[96:99], v[64:79]
	ds_read_b128 v[80:83], v205 offset:32768
	ds_read_b128 v[144:147], v205 offset:36864
	ds_read_b128 v[112:115], v206 offset:32768
	ds_read_b128 v[124:127], v206 offset:36864
	s_waitcnt lgkmcnt(3)
	v_mfma_f32_32x32x16_bf16 v[80:95], v[80:83], v[108:111], 0
	s_waitcnt lgkmcnt(1)
	v_mfma_f32_32x32x16_bf16 v[80:95], v[112:115], v[104:107], v[80:95]
	ds_read_b128 v[112:115], v207 offset:32768
	ds_read_b128 v[120:123], v207 offset:36864
	s_waitcnt lgkmcnt(1)
	v_mfma_f32_32x32x16_bf16 v[80:95], v[112:115], v[100:103], v[80:95]
	ds_read_b128 v[116:119], v208 offset:32768
	ds_read_b128 v[112:115], v208 offset:36864
	s_waitcnt lgkmcnt(1)
	v_mfma_f32_32x32x16_bf16 v[80:95], v[116:119], v[96:99], v[80:95]
	v_exp_f32_e32 v195, v64
	v_exp_f32_e32 v193, v65
	v_exp_f32_e32 v194, v66
	v_exp_f32_e32 v192, v67
	v_exp_f32_e32 v191, v68
	v_exp_f32_e32 v189, v69
	v_exp_f32_e32 v190, v70
	v_exp_f32_e32 v188, v71
	v_exp_f32_e32 v187, v72
	v_exp_f32_e32 v185, v73
	v_exp_f32_e32 v186, v74
	v_exp_f32_e32 v184, v75
	v_exp_f32_e32 v183, v76
	v_exp_f32_e32 v181, v77
	v_exp_f32_e32 v182, v78
	v_exp_f32_e32 v180, v79
	v_cvt_pk_bf16_f32 v64, v179, v177
	v_cvt_pk_bf16_f32 v65, v178, v176
	v_cvt_pk_bf16_f32 v66, v175, v173
	v_cvt_pk_bf16_f32 v67, v174, v172
	v_cvt_pk_bf16_f32 v148, v171, v169
	v_cvt_pk_bf16_f32 v149, v170, v168
	v_cvt_pk_bf16_f32 v150, v167, v165
	v_cvt_pk_bf16_f32 v151, v166, v164
	s_nop 0
	v_permlane32_swap_b32_e32 v64, v66
	v_permlane32_swap_b32_e32 v65, v67
	v_permlane32_swap_b32_e32 v148, v150
	v_permlane32_swap_b32_e32 v149, v151
	v_cvt_pk_bf16_f32 v196, v195, v193
	v_cvt_pk_bf16_f32 v197, v194, v192
	v_cvt_pk_bf16_f32 v198, v191, v189
	v_cvt_pk_bf16_f32 v199, v190, v188
	v_cvt_pk_bf16_f32 v116, v187, v185
	v_cvt_pk_bf16_f32 v117, v186, v184
	v_cvt_pk_bf16_f32 v118, v183, v181
	v_cvt_pk_bf16_f32 v119, v182, v180
	s_nop 0
	v_permlane32_swap_b32_e32 v196, v198
	v_permlane32_swap_b32_e32 v197, v199
	v_permlane32_swap_b32_e32 v116, v118
	v_permlane32_swap_b32_e32 v117, v119
	ds_read_b64_tr_b16 v[68:69], v204 offset:0
	ds_read_b64_tr_b16 v[70:71], v204 offset:0x800
	ds_read_b64_tr_b16 v[72:73], v204 offset:0x1000
	ds_read_b64_tr_b16 v[74:75], v204 offset:0x1800
	ds_read_b64_tr_b16 v[76:77], v204 offset:0x2000
	ds_read_b64_tr_b16 v[78:79], v204 offset:0x2800
	ds_read_b64_tr_b16 v[156:157], v204 offset:0x3000
	ds_read_b64_tr_b16 v[158:159], v204 offset:0x3800
	s_waitcnt lgkmcnt(0)
	s_nop 0
	v_mfma_f32_32x32x16_bf16 v[0:15], v[64:67], v[68:71], v[0:15]
	ds_read_b64_tr_b16 v[68:69], v204 offset:0x200
	ds_read_b64_tr_b16 v[70:71], v204 offset:0xa00
	v_mfma_f32_32x32x16_bf16 v[0:15], v[148:151], v[72:75], v[0:15]
	ds_read_b64_tr_b16 v[72:73], v204 offset:0x1200
	ds_read_b64_tr_b16 v[74:75], v204 offset:0x1a00
	v_mfma_f32_32x32x16_bf16 v[0:15], v[196:199], v[76:79], v[0:15]
	ds_read_b64_tr_b16 v[76:77], v204 offset:0x2200
	ds_read_b64_tr_b16 v[78:79], v204 offset:0x2a00
	ds_read_b64_tr_b16 v[160:161], v204 offset:0x3200
	ds_read_b64_tr_b16 v[162:163], v204 offset:0x3a00
	s_waitcnt lgkmcnt(0)
	v_mfma_f32_32x32x16_bf16 v[0:15], v[116:119], v[156:159], v[0:15]
	v_mfma_f32_32x32x16_bf16 v[16:31], v[64:67], v[68:71], v[16:31]
	ds_read_b64_tr_b16 v[68:69], v204 offset:0x400
	ds_read_b64_tr_b16 v[70:71], v204 offset:0xc00
	v_mfma_f32_32x32x16_bf16 v[16:31], v[148:151], v[72:75], v[16:31]
	ds_read_b64_tr_b16 v[72:73], v204 offset:0x1400
	ds_read_b64_tr_b16 v[74:75], v204 offset:0x1c00
	v_mfma_f32_32x32x16_bf16 v[16:31], v[196:199], v[76:79], v[16:31]
	ds_read_b64_tr_b16 v[76:77], v204 offset:0x2400
	ds_read_b64_tr_b16 v[78:79], v204 offset:0x2c00
	ds_read_b64_tr_b16 v[156:157], v204 offset:0x3400
	ds_read_b64_tr_b16 v[158:159], v204 offset:0x3c00
	s_waitcnt lgkmcnt(0)
	v_mfma_f32_32x32x16_bf16 v[16:31], v[116:119], v[160:163], v[16:31]
	v_mfma_f32_32x32x16_bf16 v[32:47], v[64:67], v[68:71], v[32:47]
	ds_read_b64_tr_b16 v[68:69], v204 offset:0x600
	ds_read_b64_tr_b16 v[70:71], v204 offset:0xe00
	ds_read_b64_tr_b16 v[210:211], v204 offset:0x1600
	ds_read_b64_tr_b16 v[212:213], v204 offset:0x1e00
	ds_read_b64_tr_b16 v[214:215], v204 offset:0x2600
	ds_read_b64_tr_b16 v[216:217], v204 offset:0x2e00
	ds_read_b64_tr_b16 v[224:225], v204 offset:0x3600
	v_mfma_f32_32x32x16_bf16 v[32:47], v[148:151], v[72:75], v[32:47]
	ds_read_b64_tr_b16 v[226:227], v204 offset:0x3e00
	s_waitcnt lgkmcnt(0)
; #define SBAR() __builtin_amdgcn_sched_barrier(0)
; #define DMA_V(t, buf) do { const char* vb_ = (const char*)Vh + (size_t)(t) * TILEB; \
;         glds16(vb_ + vsrc[0], (unsigned)__builtin_amdgcn_readfirstlane(lds0 + (buf) * SHM_V + widu * 2048)); \
;         glds16(vb_ + vsrc[1], (unsigned)__builtin_amdgcn_readfirstlane(lds0 + (buf) * SHM_V + widu * 2048 + 1024)); } while (0)
; #define WBAR0() do { asm volatile("s_waitcnt vmcnt(0)" ::: "memory"); __syncthreads(); } while (0)
; #define EXPH(P) do { _Pragma("unroll") for (int r = 0; r < 16; ++r) P[r] = __builtin_amdgcn_exp2f(P[r]); } while (0)
; template <bool FAST> __device__ __forceinline__ void finishSM(f32x16& p0, f32x16& p1, float alpha, float& l_reg, bf16x8& pa0, bf16x8& pa1, bf16x8& pa2, bf16x8& pa3) {
;     if (FAST) SBAR();
; #pragma unroll
;     for (int r = 0; r < 16; ++r) p1[r] = __builtin_amdgcn_exp2f(p1[r]);
;     float ps = 0;
;     if (FAST) { float s0 = 0.f, s1 = 0.f, s2 = 0.f, s3 = 0.f;
; #pragma unroll
;         for (int r = 0; r < 16; r += 4) { s0 += p0[r] + p1[r]; s1 += p0[r + 1] + p1[r + 1]; s2 += p0[r + 2] + p1[r + 2]; s3 += p0[r + 3] + p1[r + 3]; }
;         ps = (s0 + s1) + (s2 + s3); }
;     else {
; #pragma unroll
;     for (int r = 0; r < 16; ++r) ps += p0[r];
; #pragma unroll
;     for (int r = 0; r < 16; ++r) ps += p1[r];
;     }
;     if (FAST) { SBAR(); l_reg += ps; }
;     else { auto rr = __builtin_amdgcn_permlane32_swap(__float_as_uint(ps), __float_as_uint(ps), false, false);
;            ps = __uint_as_float(rr[0]) + __uint_as_float(rr[1]); l_reg = l_reg * alpha + ps; }
;     ...
;     PK4(p0, 0, pa0); PK4(p0, 8, pa1); PK4(p1, 0, pa2); PK4(p1, 8, pa3);
;     ...
;         SBAR(); qkt_mix<DQK, NREG>(pA0, pA1, K_lds, qr, qs, r32, hi);
;         finishSM<true>(pB0, pB1, dummy_a, l_reg, pa0, pa1, pa2, pa3); SBAR();
;         pv_d0(o, vb0 + SHM_V, pa0, pa1, pa2, pa3);
;         if (!isY) { EXPH(pA0); }
;         WBAR0();
;     }
;     DMA_V(NT - 1, 1); SBAR();
;     if (isY) { EXPH(pA0); }
;     SBAR(); qkt_mix<DQK, NREG>(pB0, pB1, K_lds + SHM_K, qr, qs, r32, hi);
;     finishSM<true>(pA0, pA1, dummy_a, l_reg, pa0, pa1, pa2, pa3); SBAR();
	v_mfma_f32_32x32x16_bf16 v[32:47], v[196:199], v[76:79], v[32:47]
	v_mfma_f32_32x32x16_bf16 v[32:47], v[116:119], v[156:159], v[32:47]
	v_mfma_f32_32x32x16_bf16 v[48:63], v[64:67], v[68:71], v[48:63]
	v_exp_f32_e32 v163, v80
	v_exp_f32_e32 v161, v81
	v_exp_f32_e32 v162, v82
	v_exp_f32_e32 v160, v83
	v_add_f32_e32 v80, v178, v194
	v_add_f32_e32 v81, v179, v195
	v_add_f32_e32 v82, v176, v192
	v_add_f32_e32 v83, v177, v193
	v_exp_f32_e32 v159, v84
	v_mfma_f32_32x32x16_bf16 v[64:79], v[144:147], v[108:111], 0
	v_exp_f32_e32 v157, v85
	v_exp_f32_e32 v158, v86
	v_exp_f32_e32 v156, v87
	v_add_f32_e32 v84, v174, v190
	v_add_f32_e32 v85, v175, v191
	v_add_f32_e32 v86, v172, v188
	v_add_f32_e32 v87, v173, v189
	v_mfma_f32_32x32x16_bf16 v[48:63], v[148:151], v[210:213], v[48:63]
	v_exp_f32_e32 v151, v88
	v_exp_f32_e32 v149, v89
	v_exp_f32_e32 v150, v90
	v_exp_f32_e32 v148, v91
	v_add_f32_e32 v88, v170, v186
	v_add_f32_e32 v89, v171, v187
	v_add_f32_e32 v90, v168, v184
	v_add_f32_e32 v91, v169, v185
	v_add_f32_e32 v80, v84, v80
	v_add_f32_e32 v81, v85, v81
	v_mfma_f32_32x32x16_bf16 v[64:79], v[124:127], v[104:107], v[64:79]
	v_add_f32_e64 v82, v86, v82
	v_add_f32_e64 v83, v87, v83
	v_exp_f32_e32 v147, v92
	v_exp_f32_e32 v145, v93
	v_exp_f32_e32 v146, v94
	v_exp_f32_e32 v144, v95
	v_add_f32_e32 v92, v166, v182
	v_add_f32_e32 v93, v167, v183
	v_add_f32_e32 v94, v164, v180
	v_add_f32_e32 v95, v165, v181
	v_mfma_f32_32x32x16_bf16 v[48:63], v[196:199], v[214:217], v[48:63]
	v_add_f32_e64 v80, v88, v80
	v_add_f32_e64 v81, v89, v81
	v_add_f32_e64 v82, v90, v82
	v_add_f32_e64 v83, v91, v83
	s_add_i32 s1, s1, 2
	v_add_f32_e32 v80, v92, v80
	v_add_f32_e32 v81, v93, v81
	v_add_f32_e32 v82, v94, v82
	v_add_f32_e32 v83, v95, v83
	s_waitcnt vmcnt(0)
	s_add_u32 s46, s46, 0xc0000
	v_mfma_f32_32x32x16_bf16 v[64:79], v[120:123], v[100:103], v[64:79]
	v_add_f32_e64 v80, v82, v80
	v_add_f32_e64 v81, v83, v81
	v_add_f32_e32 v124, v134, v141
	s_addc_u32 s47, s47, 0
	v_add_f32_e32 v80, v80, v81
	v_lshl_add_u64 v[142:143], v[142:143], 0, s[28:29]
	s_cmp_gt_u32 s1, 64
	v_add_f32_e32 v134, v124, v80
	v_mfma_f32_32x32x16_bf16 v[48:63], v[116:119], v[224:227], v[48:63]
	s_waitcnt lgkmcnt(0)
	s_barrier
	v_mfma_f32_32x32x16_bf16 v[64:79], v[112:115], v[96:99], v[64:79]
	s_cbranch_scc0 .LBB0_567
	s_cmp_lg_u32 0, -1
	s_cselect_b32 s0, 0, 0
	s_add_i32 s0, s0, s49
	s_add_i32 s1, s0, 0x4000
	s_mov_b32 s46, m0
	s_mov_b32 m0, s1
	s_nop 0
	global_load_lds_dwordx4 v[152:153], off
	s_mov_b32 m0, s46
	s_addk_i32 s0, 0x4400
	s_mov_b32 s1, m0
	s_mov_b32 m0, s0
	s_nop 0
	global_load_lds_dwordx4 v[154:155], off
	s_mov_b32 m0, s1
	ds_read_b128 v[80:83], v205 offset:40960
	ds_read_b128 v[124:127], v205 offset:45056
	ds_read_b128 v[112:115], v206 offset:40960
	ds_read_b128 v[120:123], v206 offset:45056
	s_waitcnt lgkmcnt(3)
	v_mfma_f32_32x32x16_bf16 v[80:95], v[80:83], v[108:111], 0
	s_waitcnt lgkmcnt(1)
	v_mfma_f32_32x32x16_bf16 v[80:95], v[112:115], v[104:107], v[80:95]
	ds_read_b128 v[112:115], v207 offset:40960
	ds_read_b128 v[116:119], v207 offset:45056
	s_waitcnt lgkmcnt(1)
	v_mfma_f32_32x32x16_bf16 v[80:95], v[112:115], v[100:103], v[80:95]
	ds_read_b128 v[152:155], v208 offset:40960
	ds_read_b128 v[112:115], v208 offset:45056
	s_waitcnt lgkmcnt(1)
	v_mfma_f32_32x32x16_bf16 v[80:95], v[152:155], v[96:99], v[80:95]
	v_exp_f32_e32 v143, v66
	v_exp_f32_e32 v152, v67
	v_exp_f32_e32 v155, v70
	v_exp_f32_e32 v164, v71
	v_exp_f32_e32 v167, v74
	v_exp_f32_e32 v141, v64
	v_exp_f32_e32 v168, v75
	v_add_f32_e32 v64, v162, v143
	v_exp_f32_e32 v142, v65
	v_exp_f32_e32 v171, v78
	v_add_f32_e32 v64, 0, v64
	v_add_f32_e32 v65, v160, v152
	v_add_f32_e32 v66, v158, v155
	v_exp_f32_e32 v79, v79
	v_add_f32_e32 v65, 0, v65
	v_add_f32_e32 v64, v66, v64
	v_add_f32_e32 v66, v156, v164
	v_add_f32_e32 v65, v66, v65
	v_add_f32_e32 v66, v150, v167
	v_exp_f32_e32 v153, v68
	v_exp_f32_e32 v154, v69
	v_exp_f32_e32 v165, v72
	v_exp_f32_e32 v166, v73
	v_exp_f32_e32 v169, v76
	v_exp_f32_e32 v170, v77
	v_add_f32_e32 v64, v66, v64
	v_add_f32_e32 v66, v148, v168
	v_add_f32_e32 v65, v66, v65
	v_add_f32_e32 v66, v146, v171
	v_add_f32_e32 v64, v66, v64
	v_add_f32_e32 v66, v144, v79
	v_add_f32_e32 v65, v66, v65
	v_add_f32_e32 v172, v163, v141
	v_add_f32_e32 v173, v161, v142
	v_add_f32_e32 v174, v159, v153
	v_add_f32_e32 v175, v157, v154
	v_add_f32_e32 v176, v151, v165
	v_add_f32_e32 v177, v149, v166
	v_add_f32_e32 v178, v147, v169
	v_add_f32_e32 v179, v145, v170
	v_add_f32_e32 v180, v65, v64
	v_cvt_pk_bf16_f32 v64, v163, v161
	v_cvt_pk_bf16_f32 v65, v162, v160
	v_cvt_pk_bf16_f32 v66, v159, v157
	v_cvt_pk_bf16_f32 v67, v158, v156
	v_cvt_pk_bf16_f32 v68, v151, v149
	v_cvt_pk_bf16_f32 v69, v150, v148
	v_cvt_pk_bf16_f32 v70, v147, v145
	v_cvt_pk_bf16_f32 v71, v146, v144
	s_nop 0
	v_permlane32_swap_b32_e32 v64, v66
	v_permlane32_swap_b32_e32 v65, v67
	v_permlane32_swap_b32_e32 v68, v70
	v_permlane32_swap_b32_e32 v69, v71
	v_cvt_pk_bf16_f32 v72, v141, v142
	v_cvt_pk_bf16_f32 v73, v143, v152
	v_cvt_pk_bf16_f32 v74, v153, v154
	v_cvt_pk_bf16_f32 v75, v155, v164
	v_cvt_pk_bf16_f32 v76, v165, v166
	v_cvt_pk_bf16_f32 v77, v167, v168
	v_cvt_pk_bf16_f32 v78, v169, v170
	v_cvt_pk_bf16_f32 v79, v171, v79
	s_nop 0
	v_permlane32_swap_b32_e32 v72, v74
	v_permlane32_swap_b32_e32 v73, v75
	v_permlane32_swap_b32_e32 v76, v78
	v_permlane32_swap_b32_e32 v77, v79
	ds_read_b64_tr_b16 v[142:143], v203 offset:0
	ds_read_b64_tr_b16 v[144:145], v203 offset:0x800
	ds_read_b64_tr_b16 v[146:147], v203 offset:0x1000
	ds_read_b64_tr_b16 v[148:149], v203 offset:0x1800
	ds_read_b64_tr_b16 v[150:151], v203 offset:0x2000
	ds_read_b64_tr_b16 v[152:153], v203 offset:0x2800
	ds_read_b64_tr_b16 v[154:155], v203 offset:0x3000
	ds_read_b64_tr_b16 v[156:157], v203 offset:0x3800
	s_waitcnt lgkmcnt(0)
; #define SBAR() __builtin_amdgcn_sched_barrier(0)
; #define WBAR0() do { asm volatile("s_waitcnt vmcnt(0)" ::: "memory"); __syncthreads(); } while (0)
; #define EXPH(P) do { _Pragma("unroll") for (int r = 0; r < 16; ++r) P[r] = __builtin_amdgcn_exp2f(P[r]); } while (0)
; template <int D0> __device__ __forceinline__ void pv_one(f32x16& od, int vb, bf16x8 pa0, bf16x8 pa1, bf16x8 pa2, bf16x8 pa3) {
;     const s16x4 l0 = tr_read<v_rd_off(D0, 0, 0)>(vb), h0 = tr_read<v_rd_off(D0, 0, 1)>(vb), l1 = tr_read<v_rd_off(D0, 1, 0)>(vb), h1 = tr_read<v_rd_off(D0, 1, 1)>(vb);
;     const s16x4 l2 = tr_read<v_rd_off(D0, 2, 0)>(vb), h2 = tr_read<v_rd_off(D0, 2, 1)>(vb), l3 = tr_read<v_rd_off(D0, 3, 0)>(vb), h3 = tr_read<v_rd_off(D0, 3, 1)>(vb);
;     asm volatile("s_waitcnt lgkmcnt(0)" ::: "memory"); SBAR();
;     ...
;     od = __builtin_amdgcn_mfma_f32_32x32x16_bf16(pa0, PK(l0, h0), od, 0, 0, 0);
;     od = __builtin_amdgcn_mfma_f32_32x32x16_bf16(pa1, PK(l1, h1), od, 0, 0, 0);
;     od = __builtin_amdgcn_mfma_f32_32x32x16_bf16(pa2, PK(l2, h2), od, 0, 0, 0);
;     od = __builtin_amdgcn_mfma_f32_32x32x16_bf16(pa3, PK(l3, h3), od, 0, 0, 0);
;     ...
; }
; __device__ __forceinline__ void pv_d0(f32x16* o, int vb, bf16x8 pa0, bf16x8 pa1, bf16x8 pa2, bf16x8 pa3) {
;     pv_one<0>(o[0], vb, pa0, pa1, pa2, pa3); pv_one<1>(o[1], vb, pa0, pa1, pa2, pa3); pv_one<2>(o[2], vb, pa0, pa1, pa2, pa3); pv_one<3>(o[3], vb, pa0, pa1, pa2, pa3);
;     ...
;     pv_d0(o, vb0, pa0, pa1, pa2, pa3);
;     if (!isY) { EXPH(pB0); }
;     WBAR0();
	s_nop 0
	v_mfma_f32_32x32x16_bf16 v[0:15], v[64:67], v[142:145], v[0:15]
	ds_read_b64_tr_b16 v[142:143], v203 offset:0x200
	ds_read_b64_tr_b16 v[144:145], v203 offset:0xa00
	v_mfma_f32_32x32x16_bf16 v[0:15], v[68:71], v[146:149], v[0:15]
	ds_read_b64_tr_b16 v[146:147], v203 offset:0x1200
	ds_read_b64_tr_b16 v[148:149], v203 offset:0x1a00
	v_mfma_f32_32x32x16_bf16 v[0:15], v[72:75], v[150:153], v[0:15]
	ds_read_b64_tr_b16 v[150:151], v203 offset:0x2200
	ds_read_b64_tr_b16 v[152:153], v203 offset:0x2a00
	ds_read_b64_tr_b16 v[158:159], v203 offset:0x3200
	ds_read_b64_tr_b16 v[160:161], v203 offset:0x3a00
	s_waitcnt lgkmcnt(0)
	v_mfma_f32_32x32x16_bf16 v[0:15], v[76:79], v[154:157], v[0:15]
	v_mfma_f32_32x32x16_bf16 v[16:31], v[64:67], v[142:145], v[16:31]
	ds_read_b64_tr_b16 v[142:143], v203 offset:0x400
	ds_read_b64_tr_b16 v[144:145], v203 offset:0xc00
	v_mfma_f32_32x32x16_bf16 v[16:31], v[68:71], v[146:149], v[16:31]
	ds_read_b64_tr_b16 v[146:147], v203 offset:0x1400
	ds_read_b64_tr_b16 v[148:149], v203 offset:0x1c00
	v_mfma_f32_32x32x16_bf16 v[16:31], v[72:75], v[150:153], v[16:31]
	ds_read_b64_tr_b16 v[150:151], v203 offset:0x2400
	ds_read_b64_tr_b16 v[152:153], v203 offset:0x2c00
	ds_read_b64_tr_b16 v[154:155], v203 offset:0x3400
	ds_read_b64_tr_b16 v[156:157], v203 offset:0x3c00
	s_waitcnt lgkmcnt(0)
	v_mfma_f32_32x32x16_bf16 v[16:31], v[76:79], v[158:161], v[16:31]
	v_mfma_f32_32x32x16_bf16 v[32:47], v[64:67], v[142:145], v[32:47]
	ds_read_b64_tr_b16 v[142:143], v203 offset:0x600
	ds_read_b64_tr_b16 v[144:145], v203 offset:0xe00
	v_mfma_f32_32x32x16_bf16 v[32:47], v[68:71], v[146:149], v[32:47]
	ds_read_b64_tr_b16 v[146:147], v203 offset:0x1600
	ds_read_b64_tr_b16 v[148:149], v203 offset:0x1e00
	v_mfma_f32_32x32x16_bf16 v[32:47], v[72:75], v[150:153], v[32:47]
	ds_read_b64_tr_b16 v[150:151], v203 offset:0x2600
	ds_read_b64_tr_b16 v[152:153], v203 offset:0x2e00
	ds_read_b64_tr_b16 v[158:159], v203 offset:0x3600
	ds_read_b64_tr_b16 v[160:161], v203 offset:0x3e00
	s_waitcnt lgkmcnt(0)
	v_mfma_f32_32x32x16_bf16 v[32:47], v[76:79], v[154:157], v[32:47]
	v_mfma_f32_32x32x16_bf16 v[48:63], v[64:67], v[142:145], v[48:63]
	s_waitcnt vmcnt(0)
	v_exp_f32_e32 v80, v80
	v_exp_f32_e32 v81, v81
	v_exp_f32_e32 v82, v82
	v_exp_f32_e32 v83, v83
	v_exp_f32_e32 v84, v84
	v_exp_f32_e32 v85, v85
	v_mfma_f32_32x32x16_bf16 v[48:63], v[68:71], v[146:149], v[48:63]
	v_exp_f32_e32 v86, v86
	v_exp_f32_e32 v87, v87
	v_exp_f32_e32 v88, v88
	v_exp_f32_e32 v89, v89
	v_exp_f32_e32 v90, v90
	v_exp_f32_e32 v91, v91
	v_exp_f32_e32 v92, v92
	v_mfma_f32_32x32x16_bf16 v[48:63], v[72:75], v[150:153], v[48:63]
	v_exp_f32_e32 v93, v93
	v_exp_f32_e32 v94, v94
	v_exp_f32_e32 v95, v95
	s_waitcnt lgkmcnt(0)
	s_barrier
; #define SBAR() __builtin_amdgcn_sched_barrier(0)
; #define WBAR0() do { asm volatile("s_waitcnt vmcnt(0)" ::: "memory"); __syncthreads(); } while (0)
; #define EXPH(P) do { _Pragma("unroll") for (int r = 0; r < 16; ++r) P[r] = __builtin_amdgcn_exp2f(P[r]); } while (0)
;     ...
;     SBAR(); qkt_mix<DQK, NREG>(pB0, pB1, K_lds + SHM_K, qr, qs, r32, hi);
;     finishSM<true>(pA0, pA1, dummy_a, l_reg, pa0, pa1, pa2, pa3); SBAR();
;     pv_d0(o, vb0, pa0, pa1, pa2, pa3);
;     if (!isY) { EXPH(pB0); }
;     WBAR0();
;     if (isY) { EXPH(pB0); }
;     SBAR(); finishSM<true>(pB0, pB1, dummy_a, l_reg, pa0, pa1, pa2, pa3); SBAR();
;     pv_d0(o, vb0 + SHM_V, pa0, pa1, pa2, pa3);
;     __builtin_amdgcn_s_setprio(0);
;     (void)dummy_m;
;     { auto rr = __builtin_amdgcn_permlane32_swap(__float_as_uint(l_reg), __float_as_uint(l_reg), false, false); l_reg = __uint_as_float(rr[0]) + __uint_as_float(rr[1]); }
;     {
;         int t2 = threadIdx.x; asm volatile("" : "+v"(t2));
;         const int wid2 = t2 >> 6, lane2 = t2 & 63, r32b = lane2 & 31, hib = lane2 >> 5;
;         float* li2 = (float*)(lds + OFF_WS) + wid2 * 64;
;         if (hib == 0) li2[r32b] = l_reg; asm volatile("s_waitcnt lgkmcnt(0)" ::: "memory");
	v_mfma_f32_32x32x16_bf16 v[48:63], v[76:79], v[158:161], v[48:63]
	v_mfma_f32_32x32x16_bf16 v[64:79], v[124:127], v[108:111], 0
	v_mfma_f32_32x32x16_bf16 v[64:79], v[120:123], v[104:107], v[64:79]
	v_add_f32_e32 v104, 0, v172
	v_add_f32_e32 v105, 0, v173
	v_add_f32_e32 v104, v174, v104
	v_add_f32_e32 v105, v175, v105
	v_add_f32_e32 v104, v176, v104
	v_add_f32_e32 v105, v177, v105
	v_add_f32_e32 v104, v178, v104
	v_mfma_f32_32x32x16_bf16 v[64:79], v[116:119], v[100:103], v[64:79]
	v_add_f32_e32 v100, v179, v105
	v_add_f32_e32 v100, v100, v104
	v_add_f32_e32 v100, v180, v100
	v_add_f32_e32 v100, v134, v100
	v_mfma_f32_32x32x16_bf16 v[64:79], v[112:115], v[96:99], v[64:79]
	s_nop 11
	v_exp_f32_e32 v64, v64
	v_exp_f32_e32 v65, v65
	v_exp_f32_e32 v97, v68
	v_exp_f32_e32 v96, v66
	v_exp_f32_e32 v98, v69
	v_exp_f32_e32 v67, v67
	v_exp_f32_e32 v99, v70
	v_exp_f32_e32 v101, v71
	v_add_f32_e32 v66, v80, v64
	v_exp_f32_e32 v102, v72
	v_add_f32_e32 v66, 0, v66
	v_add_f32_e32 v68, v81, v65
	v_add_f32_e32 v71, v84, v97
	v_exp_f32_e32 v103, v73
	v_add_f32_e32 v68, 0, v68
	v_add_f32_e32 v69, v82, v96
	v_add_f32_e32 v66, v71, v66
	v_add_f32_e32 v71, v85, v98
	v_exp_f32_e32 v104, v74
	v_add_f32_e32 v69, 0, v69
	v_add_f32_e32 v70, v83, v67
	v_add_f32_e32 v68, v71, v68
	v_add_f32_e32 v71, v86, v99
	v_exp_f32_e32 v105, v75
	v_add_f32_e32 v70, 0, v70
	v_add_f32_e32 v69, v71, v69
	v_add_f32_e32 v71, v87, v101
	v_exp_f32_e32 v106, v76
	v_add_f32_e32 v70, v71, v70
	v_add_f32_e32 v71, v88, v102
	v_exp_f32_e32 v107, v77
	v_add_f32_e32 v66, v71, v66
	v_add_f32_e32 v71, v89, v103
	v_exp_f32_e32 v108, v78
	v_add_f32_e32 v68, v71, v68
	v_add_f32_e32 v71, v90, v104
	v_exp_f32_e32 v109, v79
	v_add_f32_e32 v69, v71, v69
	v_add_f32_e32 v71, v91, v105
	v_add_f32_e32 v70, v71, v70
	v_add_f32_e32 v71, v92, v106
	v_add_f32_e32 v66, v71, v66
	v_add_f32_e32 v71, v93, v107
	v_add_f32_e32 v68, v71, v68
	v_add_f32_e32 v71, v94, v108
	v_add_f32_e32 v69, v71, v69
	v_add_f32_e32 v71, v95, v109
	v_add_f32_e32 v70, v71, v70
	v_add_f32_e32 v66, v68, v66
	v_add_f32_e32 v68, v70, v69
	v_add_f32_e32 v66, v68, v66
	v_cvt_pk_bf16_f32 v68, v80, v81
	v_cvt_pk_bf16_f32 v69, v82, v83
	v_cvt_pk_bf16_f32 v70, v84, v85
	v_cvt_pk_bf16_f32 v71, v86, v87
	v_add_f32_e32 v66, v100, v66
	v_permlane32_swap_b32_e32 v68, v70
	v_permlane32_swap_b32_e32 v69, v71
	v_cvt_pk_bf16_f32 v72, v88, v89
	v_cvt_pk_bf16_f32 v73, v90, v91
	v_cvt_pk_bf16_f32 v74, v92, v93
	v_cvt_pk_bf16_f32 v75, v94, v95
	v_cvt_pk_bf16_f32 v76, v64, v65
	v_cvt_pk_bf16_f32 v77, v96, v67
	v_cvt_pk_bf16_f32 v78, v97, v98
	v_cvt_pk_bf16_f32 v79, v99, v101
	v_cvt_pk_bf16_f32 v80, v102, v103
	v_cvt_pk_bf16_f32 v81, v104, v105
	v_cvt_pk_bf16_f32 v82, v106, v107
	v_cvt_pk_bf16_f32 v83, v108, v109
	s_nop 0
	v_permlane32_swap_b32_e32 v72, v74
	v_permlane32_swap_b32_e32 v73, v75
	v_permlane32_swap_b32_e32 v76, v78
	v_permlane32_swap_b32_e32 v77, v79
	v_permlane32_swap_b32_e32 v80, v82
	v_permlane32_swap_b32_e32 v81, v83
	ds_read_b64_tr_b16 v[84:85], v204 offset:0
	ds_read_b64_tr_b16 v[86:87], v204 offset:0x800
	ds_read_b64_tr_b16 v[88:89], v204 offset:0x1000
	ds_read_b64_tr_b16 v[90:91], v204 offset:0x1800
	ds_read_b64_tr_b16 v[92:93], v204 offset:0x2000
	ds_read_b64_tr_b16 v[94:95], v204 offset:0x2800
	ds_read_b64_tr_b16 v[96:97], v204 offset:0x3000
	ds_read_b64_tr_b16 v[98:99], v204 offset:0x3800
	s_waitcnt lgkmcnt(0)
	s_nop 0
	v_mfma_f32_32x32x16_bf16 v[0:15], v[68:71], v[84:87], v[0:15]
	ds_read_b64_tr_b16 v[84:85], v204 offset:0x200
	ds_read_b64_tr_b16 v[86:87], v204 offset:0xa00
	v_mfma_f32_32x32x16_bf16 v[0:15], v[72:75], v[88:91], v[0:15]
	ds_read_b64_tr_b16 v[88:89], v204 offset:0x1200
	ds_read_b64_tr_b16 v[90:91], v204 offset:0x1a00
	v_mfma_f32_32x32x16_bf16 v[0:15], v[76:79], v[92:95], v[0:15]
	ds_read_b64_tr_b16 v[92:93], v204 offset:0x2200
	ds_read_b64_tr_b16 v[94:95], v204 offset:0x2a00
	ds_read_b64_tr_b16 v[100:101], v204 offset:0x3200
	ds_read_b64_tr_b16 v[102:103], v204 offset:0x3a00
	s_waitcnt lgkmcnt(0)
	v_mfma_f32_32x32x16_bf16 v[0:15], v[80:83], v[96:99], v[0:15]
	v_mfma_f32_32x32x16_bf16 v[16:31], v[68:71], v[84:87], v[16:31]
	ds_read_b64_tr_b16 v[84:85], v204 offset:0x400
	ds_read_b64_tr_b16 v[86:87], v204 offset:0xc00
	v_mfma_f32_32x32x16_bf16 v[16:31], v[72:75], v[88:91], v[16:31]
	ds_read_b64_tr_b16 v[88:89], v204 offset:0x1400
	ds_read_b64_tr_b16 v[90:91], v204 offset:0x1c00
	v_mfma_f32_32x32x16_bf16 v[16:31], v[76:79], v[92:95], v[16:31]
	ds_read_b64_tr_b16 v[92:93], v204 offset:0x2400
	ds_read_b64_tr_b16 v[94:95], v204 offset:0x2c00
	ds_read_b64_tr_b16 v[96:97], v204 offset:0x3400
	ds_read_b64_tr_b16 v[98:99], v204 offset:0x3c00
	s_waitcnt lgkmcnt(0)
	v_mfma_f32_32x32x16_bf16 v[16:31], v[80:83], v[100:103], v[16:31]
	v_mfma_f32_32x32x16_bf16 v[32:47], v[68:71], v[84:87], v[32:47]
	ds_read_b64_tr_b16 v[84:85], v204 offset:0x600
	ds_read_b64_tr_b16 v[86:87], v204 offset:0xe00
	v_mfma_f32_32x32x16_bf16 v[32:47], v[72:75], v[88:91], v[32:47]
	ds_read_b64_tr_b16 v[88:89], v204 offset:0x1600
	ds_read_b64_tr_b16 v[90:91], v204 offset:0x1e00
	v_mfma_f32_32x32x16_bf16 v[32:47], v[76:79], v[92:95], v[32:47]
	ds_read_b64_tr_b16 v[92:93], v204 offset:0x2600
	ds_read_b64_tr_b16 v[94:95], v204 offset:0x2e00
	ds_read_b64_tr_b16 v[100:101], v204 offset:0x3600
	ds_read_b64_tr_b16 v[102:103], v204 offset:0x3e00
	s_waitcnt lgkmcnt(0)
	v_mfma_f32_32x32x16_bf16 v[32:47], v[80:83], v[96:99], v[32:47]
	v_mfma_f32_32x32x16_bf16 v[48:63], v[68:71], v[84:87], v[48:63]
	v_mfma_f32_32x32x16_bf16 v[48:63], v[72:75], v[88:91], v[48:63]
	v_mfma_f32_32x32x16_bf16 v[48:63], v[76:79], v[92:95], v[48:63]
	v_mfma_f32_32x32x16_bf16 v[48:63], v[80:83], v[100:103], v[48:63]
	s_setprio 0
	v_mov_b32_e32 v65, v218
	v_mov_b32_e32 v69, v66
	s_nop 1
	v_permlane32_swap_b32_e32 v66, v69
	v_and_b32_e32 v64, 63, v65
	v_and_b32_e32 v68, 0x3fffffc0, v65
	v_and_b32_e32 v67, 31, v65
	v_lshl_add_u32 v68, v68, 2, s35
	v_cmp_gt_u32_e32 vcc, 32, v64
	s_and_saveexec_b64 s[0:1], vcc
	s_cbranch_execz .LBB0_557
	v_add_f32_e32 v66, v66, v69
	v_lshl_add_u32 v69, v67, 2, v68
	ds_write_b32 v69, v66
	s_branch .LBB0_557
